# software-pipelined k-loop (loads one full step ahead, LDS frag prefetch) in w1,w2,wout,inproj GEMMs
# speedup vs baseline: 1.0309x; 1.0309x over previous
.LBB0_27:
	s_ashr_i32 s10, s21, 31
	s_lshr_b32 s10, s10, 26
	s_add_i32 s10, s21, s10
	s_andn2_b32 s10, s10, 63
	s_sub_i32 s11, s21, s10
	s_bfe_i32 s12, s11, 0x80000
	s_bfe_u32 s12, s12, 0x3000c
	s_add_i32 s12, s11, s12
	s_bfe_i32 s13, s12, 0x80000
	s_sext_i32_i16 s13, s13
	s_and_b32 s12, s12, 0xf8
	s_sub_i32 s11, s11, s12
	s_ashr_i32 s12, s13, 3
	s_or_b32 s22, s96, s10
	s_add_i32 s22, s22, s12
	s_waitcnt vmcnt(9)
	v_mov_b32_e32 v26, v133
	s_lshl_b32 s12, s22, 7
	s_sext_i32_i8 s11, s11
	v_lshlrev_b32_e32 v16, 4, v26
	v_and_b32_e32 v0, 32, v26
	s_ashr_i32 s13, s12, 31
	v_bitop3_b32 v0, v16, v0, 48 bitop3:0x6c
	s_lshl_b32 s10, s11, 7
	s_lshl_b64 s[14:15], s[12:13], 13
	v_lshrrev_b32_e32 v17, 2, v26
	v_lshrrev_b32_e32 v2, 1, v26
	v_lshrrev_b32_e32 v0, 1, v0
	v_ashrrev_i32_e32 v4, 3, v26
	s_add_u32 s24, s3, s14
	v_and_b32_e32 v27, 0xfffffc00, v16
	v_and_or_b32 v0, v2, 32, v0
	v_bfi_b32 v4, -16, v4, v17
	s_addc_u32 s25, s18, s15
	s_ashr_i32 s11, s10, 31
	v_lshlrev_b32_e32 v0, 1, v0
	v_ashrrev_i32_e32 v5, 31, v4
	v_add_u32_e32 v8, 0x1000, v16
	v_add_u32_e32 v82, 0, v27
	s_lshl_b64 s[16:17], s[10:11], 13
	v_lshl_add_u64 v[2:3], s[24:25], 0, v[0:1]
	v_lshlrev_b64 v[4:5], 13, v[4:5]
	v_ashrrev_i32_e32 v8, 7, v8
	v_add_u32_e32 v12, 0x2000, v16
	v_readfirstlane_b32 s11, v82
	v_lshl_add_u64 v[6:7], v[2:3], 0, v[4:5]
	v_bfi_b32 v8, -16, v8, v17
	v_ashrrev_i32_e32 v12, 7, v12
	v_add_u32_e32 v16, 0x3000, v16
	s_mov_b32 m0, s11
	v_ashrrev_i32_e32 v9, 31, v8
	v_bfi_b32 v12, -16, v12, v17
	v_ashrrev_i32_e32 v16, 7, v16
	s_barrier
	global_load_lds_dwordx4 v[6:7], off
	v_add_u32_e32 v6, 0x1000, v82
	v_lshlrev_b64 v[8:9], 13, v[8:9]
	v_ashrrev_i32_e32 v13, 31, v12
	v_bfi_b32 v16, -16, v16, v17
	v_readfirstlane_b32 s11, v6
	v_add_u32_e32 v6, 0x2000, v82
	v_lshl_add_u64 v[10:11], v[2:3], 0, v[8:9]
	v_lshlrev_b64 v[12:13], 13, v[12:13]
	v_ashrrev_i32_e32 v17, 31, v16
	s_mov_b32 m0, s11
	v_readfirstlane_b32 s11, v6
	v_add_u32_e32 v6, 0x3000, v82
	v_lshl_add_u64 v[14:15], v[2:3], 0, v[12:13]
	v_lshlrev_b64 v[16:17], 13, v[16:17]
	global_load_lds_dwordx4 v[10:11], off
	s_mov_b32 m0, s11
	v_readfirstlane_b32 s11, v6
	s_add_u32 s26, s19, s16
	v_lshl_add_u64 v[2:3], v[2:3], 0, v[16:17]
	global_load_lds_dwordx4 v[14:15], off
	s_mov_b32 m0, s11
	s_addc_u32 s27, s20, s17
	global_load_lds_dwordx4 v[2:3], off
	v_add_u32_e32 v2, 0x4000, v82
	v_lshl_add_u64 v[18:19], s[26:27], 0, v[0:1]
	v_readfirstlane_b32 s11, v2
	v_add_u32_e32 v2, 0x5000, v82
	v_lshl_add_u64 v[20:21], v[18:19], 0, v[4:5]
	s_mov_b32 m0, s11
	v_readfirstlane_b32 s11, v2
	v_add_u32_e32 v2, 0x6000, v82
	v_lshl_add_u64 v[22:23], v[18:19], 0, v[8:9]
	global_load_lds_dwordx4 v[20:21], off
	s_mov_b32 m0, s11
	v_readfirstlane_b32 s11, v2
	v_add_u32_e32 v2, 0x7000, v82
	v_lshl_add_u64 v[24:25], v[18:19], 0, v[12:13]
	global_load_lds_dwordx4 v[22:23], off
	s_mov_b32 m0, s11
	v_readfirstlane_b32 s11, v2
	v_lshl_add_u64 v[18:19], v[18:19], 0, v[16:17]
	global_load_lds_dwordx4 v[24:25], off
	s_mov_b32 m0, s11
	v_and_b32_e32 v2, 15, v26
	global_load_lds_dwordx4 v[18:19], off
	v_lshlrev_b32_e32 v6, 2, v26
	v_and_b32_e32 v3, 48, v26
	v_lshlrev_b32_e32 v2, 6, v2
	v_and_b32_e32 v6, 32, v6
	v_bitop3_b32 v83, v2, v6, v3 bitop3:0x36
	v_lshlrev_b32_e32 v2, 7, v26
	v_and_b32_e32 v89, 0x2000, v2
	v_lshlrev_b32_e32 v2, 6, v26
	v_and_b32_e32 v87, 0xffffe000, v2
	v_and_b32_e32 v2, 0x3c0, v2
	v_bitop3_b32 v84, v2, v6, v3 bitop3:0x36
	v_lshl_add_u64 v[2:3], s[16:17], 0, v[16:17]
	v_or_b32_e32 v2, v2, v0
	v_lshl_add_u64 v[66:67], s[6:7], 0, v[2:3]
	v_lshl_add_u64 v[2:3], s[16:17], 0, v[12:13]
	v_or_b32_e32 v2, v2, v0
	v_lshl_add_u64 v[68:69], s[6:7], 0, v[2:3]
	v_lshl_add_u64 v[2:3], s[16:17], 0, v[8:9]
	v_or_b32_e32 v2, v2, v0
	v_lshl_add_u64 v[70:71], s[6:7], 0, v[2:3]
	v_lshl_add_u64 v[2:3], s[16:17], 0, v[4:5]
	v_or_b32_e32 v2, v2, v0
	v_lshl_add_u64 v[72:73], s[6:7], 0, v[2:3]
	v_lshl_add_u64 v[2:3], s[14:15], 0, v[16:17]
	v_or_b32_e32 v2, v2, v0
	v_lshl_add_u64 v[74:75], s[8:9], 0, v[2:3]
	v_lshl_add_u64 v[2:3], s[14:15], 0, v[12:13]
	v_or_b32_e32 v2, v2, v0
	v_lshl_add_u64 v[76:77], s[8:9], 0, v[2:3]
	v_lshl_add_u64 v[2:3], s[14:15], 0, v[8:9]
	v_or_b32_e32 v2, v2, v0
	s_waitcnt vmcnt(0)
	v_lshl_add_u64 v[78:79], s[8:9], 0, v[2:3]
	v_lshl_add_u64 v[2:3], s[14:15], 0, v[4:5]
	v_or_b32_e32 v2, v2, v0
	v_mov_b32_e32 v62, 0
	v_or_b32_e32 v85, 0x800, v87
	v_or_b32_e32 v88, 0x1000, v87
	v_or_b32_e32 v86, 0x1800, v87
	v_lshl_add_u64 v[80:81], s[8:9], 0, v[2:3]
	s_mov_b64 s[14:15], 0
	s_mov_b32 s11, 0
	v_mov_b32_e32 v63, v62
	v_mov_b32_e32 v64, v62
	v_mov_b32_e32 v65, v62
	v_mov_b32_e32 v58, v62
	v_mov_b32_e32 v59, v62
	v_mov_b32_e32 v60, v62
	v_mov_b32_e32 v61, v62
	v_mov_b32_e32 v2, v62
	v_mov_b32_e32 v3, v62
	v_mov_b32_e32 v4, v62
	v_mov_b32_e32 v5, v62
	v_mov_b32_e32 v6, v62
	v_mov_b32_e32 v7, v62
	v_mov_b32_e32 v8, v62
	v_mov_b32_e32 v9, v62
	v_mov_b32_e32 v10, v62
	v_mov_b32_e32 v11, v62
	v_mov_b32_e32 v12, v62
	v_mov_b32_e32 v13, v62
	v_mov_b32_e32 v14, v62
	v_mov_b32_e32 v15, v62
	v_mov_b32_e32 v16, v62
	v_mov_b32_e32 v17, v62
	v_mov_b32_e32 v18, v62
	v_mov_b32_e32 v19, v62
	v_mov_b32_e32 v20, v62
	v_mov_b32_e32 v21, v62
	v_mov_b32_e32 v22, v62
	v_mov_b32_e32 v23, v62
	v_mov_b32_e32 v24, v62
	v_mov_b32_e32 v25, v62
	v_mov_b32_e32 v26, v62
	v_mov_b32_e32 v27, v62
	v_mov_b32_e32 v28, v62
	v_mov_b32_e32 v29, v62
	s_waitcnt vmcnt(0)
	v_mov_b32_e32 v30, v62
	v_mov_b32_e32 v31, v62
	v_mov_b32_e32 v32, v62
	v_mov_b32_e32 v33, v62
	v_mov_b32_e32 v34, v62
	v_mov_b32_e32 v35, v62
	v_mov_b32_e32 v36, v62
	v_mov_b32_e32 v37, v62
	v_mov_b32_e32 v38, v62
	v_mov_b32_e32 v39, v62
	v_mov_b32_e32 v40, v62
	v_mov_b32_e32 v41, v62
	v_mov_b32_e32 v42, v62
	v_mov_b32_e32 v43, v62
	v_mov_b32_e32 v44, v62
	v_mov_b32_e32 v45, v62
	v_mov_b32_e32 v46, v62
	v_mov_b32_e32 v47, v62
	v_mov_b32_e32 v48, v62
	v_mov_b32_e32 v49, v62
	v_mov_b32_e32 v50, v62
	v_mov_b32_e32 v51, v62
	v_mov_b32_e32 v52, v62
	v_mov_b32_e32 v53, v62
	v_mov_b32_e32 v54, v62
	v_mov_b32_e32 v55, v62
	v_mov_b32_e32 v56, v62
	v_mov_b32_e32 v57, v62
	s_waitcnt vmcnt(0) lgkmcnt(0)
	s_barrier
	v_readfirstlane_b32 s13, v82
	v_add_u32_e32 v141, v83, v87
	v_add_u32_e32 v142, v83, v89
	ds_read_b128 v[90:93], v142 offset:16384
	ds_read_b128 v[94:97], v142 offset:18432
	ds_read_b128 v[98:101], v142 offset:20480
	ds_read_b128 v[102:105], v142 offset:22528
	ds_read_b128 v[106:109], v141
	ds_read_b128 v[110:113], v141 offset:2048
	ds_read_b128 v[114:117], v141 offset:4096
	ds_read_b128 v[118:121], v141 offset:6144
	s_add_u32 m0, s13, 0x8000
	v_lshl_add_u64 v[176:177], v[80:81], 0, s[14:15]
	global_load_lds_dwordx4 v[176:177], off
	s_add_u32 m0, s13, 0x9000
	v_lshl_add_u64 v[178:179], v[78:79], 0, s[14:15]
	global_load_lds_dwordx4 v[178:179], off
	s_add_u32 m0, s13, 0xa000
	v_lshl_add_u64 v[176:177], v[76:77], 0, s[14:15]
	global_load_lds_dwordx4 v[176:177], off
	s_add_u32 m0, s13, 0xb000
	v_lshl_add_u64 v[178:179], v[74:75], 0, s[14:15]
	global_load_lds_dwordx4 v[178:179], off
	s_add_u32 m0, s13, 0xc000
	v_lshl_add_u64 v[176:177], v[72:73], 0, s[14:15]
	global_load_lds_dwordx4 v[176:177], off
	s_add_u32 m0, s13, 0xd000
	v_lshl_add_u64 v[178:179], v[70:71], 0, s[14:15]
	global_load_lds_dwordx4 v[178:179], off
	s_add_u32 m0, s13, 0xe000
	v_lshl_add_u64 v[176:177], v[68:69], 0, s[14:15]
	global_load_lds_dwordx4 v[176:177], off
	s_add_u32 m0, s13, 0xf000
	v_lshl_add_u64 v[178:179], v[66:67], 0, s[14:15]
	global_load_lds_dwordx4 v[178:179], off
	s_add_u32 s14, s14, 0x80
	s_addc_u32 s15, s15, 0
	s_mov_b32 s16, 31
.Lgp_i28_loop:
	s_waitcnt lgkmcnt(0)
	v_mfma_f32_16x16x32_bf16 v[54:57], v[90:93], v[106:109], v[54:57]
	ds_read_b128 v[144:147], v142 offset:17408
	v_mfma_f32_16x16x32_bf16 v[50:53], v[94:97], v[106:109], v[50:53]
	ds_read_b128 v[148:151], v142 offset:19456
	v_mfma_f32_16x16x32_bf16 v[46:49], v[98:101], v[106:109], v[46:49]
	ds_read_b128 v[152:155], v142 offset:21504
	v_mfma_f32_16x16x32_bf16 v[42:45], v[102:105], v[106:109], v[42:45]
	ds_read_b128 v[156:159], v142 offset:23552
	v_mfma_f32_16x16x32_bf16 v[38:41], v[90:93], v[110:113], v[38:41]
	ds_read_b128 v[160:163], v141 offset:1024
	v_mfma_f32_16x16x32_bf16 v[34:37], v[94:97], v[110:113], v[34:37]
	ds_read_b128 v[164:167], v141 offset:3072
	v_mfma_f32_16x16x32_bf16 v[30:33], v[98:101], v[110:113], v[30:33]
	ds_read_b128 v[168:171], v141 offset:5120
	v_mfma_f32_16x16x32_bf16 v[26:29], v[102:105], v[110:113], v[26:29]
	ds_read_b128 v[172:175], v141 offset:7168
	v_mfma_f32_16x16x32_bf16 v[22:25], v[90:93], v[114:117], v[22:25]
	v_mfma_f32_16x16x32_bf16 v[18:21], v[94:97], v[114:117], v[18:21]
	v_mfma_f32_16x16x32_bf16 v[14:17], v[98:101], v[114:117], v[14:17]
	v_mfma_f32_16x16x32_bf16 v[10:13], v[102:105], v[114:117], v[10:13]
	v_mfma_f32_16x16x32_bf16 v[6:9], v[90:93], v[118:121], v[6:9]
	v_mfma_f32_16x16x32_bf16 v[2:5], v[94:97], v[118:121], v[2:5]
	v_mfma_f32_16x16x32_bf16 v[58:61], v[98:101], v[118:121], v[58:61]
	v_mfma_f32_16x16x32_bf16 v[62:65], v[102:105], v[118:121], v[62:65]
	s_waitcnt vmcnt(0) lgkmcnt(0)
	s_barrier
	v_mfma_f32_16x16x32_bf16 v[54:57], v[144:147], v[160:163], v[54:57]
	ds_read_b128 v[90:93], v142 offset:49152
	s_add_u32 m0, s13, 0x0
	v_lshl_add_u64 v[176:177], v[80:81], 0, s[14:15]
	global_load_lds_dwordx4 v[176:177], off
	v_mfma_f32_16x16x32_bf16 v[50:53], v[148:151], v[160:163], v[50:53]
	ds_read_b128 v[94:97], v142 offset:51200
	s_add_u32 m0, s13, 0x1000
	v_lshl_add_u64 v[178:179], v[78:79], 0, s[14:15]
	global_load_lds_dwordx4 v[178:179], off
	v_mfma_f32_16x16x32_bf16 v[46:49], v[152:155], v[160:163], v[46:49]
	ds_read_b128 v[98:101], v142 offset:53248
	s_add_u32 m0, s13, 0x2000
	v_lshl_add_u64 v[176:177], v[76:77], 0, s[14:15]
	global_load_lds_dwordx4 v[176:177], off
	v_mfma_f32_16x16x32_bf16 v[42:45], v[156:159], v[160:163], v[42:45]
	ds_read_b128 v[102:105], v142 offset:55296
	s_add_u32 m0, s13, 0x3000
	v_lshl_add_u64 v[178:179], v[74:75], 0, s[14:15]
	global_load_lds_dwordx4 v[178:179], off
	v_mfma_f32_16x16x32_bf16 v[38:41], v[144:147], v[164:167], v[38:41]
	ds_read_b128 v[106:109], v141 offset:32768
	s_add_u32 m0, s13, 0x4000
	v_lshl_add_u64 v[176:177], v[72:73], 0, s[14:15]
	global_load_lds_dwordx4 v[176:177], off
	v_mfma_f32_16x16x32_bf16 v[34:37], v[148:151], v[164:167], v[34:37]
	ds_read_b128 v[110:113], v141 offset:34816
	s_add_u32 m0, s13, 0x5000
	v_lshl_add_u64 v[178:179], v[70:71], 0, s[14:15]
	global_load_lds_dwordx4 v[178:179], off
	v_mfma_f32_16x16x32_bf16 v[30:33], v[152:155], v[164:167], v[30:33]
	ds_read_b128 v[114:117], v141 offset:36864
	s_add_u32 m0, s13, 0x6000
	v_lshl_add_u64 v[176:177], v[68:69], 0, s[14:15]
	global_load_lds_dwordx4 v[176:177], off
	v_mfma_f32_16x16x32_bf16 v[26:29], v[156:159], v[164:167], v[26:29]
	ds_read_b128 v[118:121], v141 offset:38912
	s_add_u32 m0, s13, 0x7000
	v_lshl_add_u64 v[178:179], v[66:67], 0, s[14:15]
	global_load_lds_dwordx4 v[178:179], off
	v_mfma_f32_16x16x32_bf16 v[22:25], v[144:147], v[168:171], v[22:25]
	v_mfma_f32_16x16x32_bf16 v[18:21], v[148:151], v[168:171], v[18:21]
	v_mfma_f32_16x16x32_bf16 v[14:17], v[152:155], v[168:171], v[14:17]
	v_mfma_f32_16x16x32_bf16 v[10:13], v[156:159], v[168:171], v[10:13]
	v_mfma_f32_16x16x32_bf16 v[6:9], v[144:147], v[172:175], v[6:9]
	v_mfma_f32_16x16x32_bf16 v[2:5], v[148:151], v[172:175], v[2:5]
	v_mfma_f32_16x16x32_bf16 v[58:61], v[152:155], v[172:175], v[58:61]
	v_mfma_f32_16x16x32_bf16 v[62:65], v[156:159], v[172:175], v[62:65]
	s_add_u32 s14, s14, 0x80
	s_addc_u32 s15, s15, 0
	s_waitcnt lgkmcnt(0)
	v_mfma_f32_16x16x32_bf16 v[54:57], v[90:93], v[106:109], v[54:57]
	ds_read_b128 v[144:147], v142 offset:50176
	v_mfma_f32_16x16x32_bf16 v[50:53], v[94:97], v[106:109], v[50:53]
	ds_read_b128 v[148:151], v142 offset:52224
	v_mfma_f32_16x16x32_bf16 v[46:49], v[98:101], v[106:109], v[46:49]
	ds_read_b128 v[152:155], v142 offset:54272
	v_mfma_f32_16x16x32_bf16 v[42:45], v[102:105], v[106:109], v[42:45]
	ds_read_b128 v[156:159], v142 offset:56320
	v_mfma_f32_16x16x32_bf16 v[38:41], v[90:93], v[110:113], v[38:41]
	ds_read_b128 v[160:163], v141 offset:33792
	v_mfma_f32_16x16x32_bf16 v[34:37], v[94:97], v[110:113], v[34:37]
	ds_read_b128 v[164:167], v141 offset:35840
	v_mfma_f32_16x16x32_bf16 v[30:33], v[98:101], v[110:113], v[30:33]
	ds_read_b128 v[168:171], v141 offset:37888
	v_mfma_f32_16x16x32_bf16 v[26:29], v[102:105], v[110:113], v[26:29]
	ds_read_b128 v[172:175], v141 offset:39936
	v_mfma_f32_16x16x32_bf16 v[22:25], v[90:93], v[114:117], v[22:25]
	v_mfma_f32_16x16x32_bf16 v[18:21], v[94:97], v[114:117], v[18:21]
	v_mfma_f32_16x16x32_bf16 v[14:17], v[98:101], v[114:117], v[14:17]
	v_mfma_f32_16x16x32_bf16 v[10:13], v[102:105], v[114:117], v[10:13]
	v_mfma_f32_16x16x32_bf16 v[6:9], v[90:93], v[118:121], v[6:9]
	v_mfma_f32_16x16x32_bf16 v[2:5], v[94:97], v[118:121], v[2:5]
	v_mfma_f32_16x16x32_bf16 v[58:61], v[98:101], v[118:121], v[58:61]
	v_mfma_f32_16x16x32_bf16 v[62:65], v[102:105], v[118:121], v[62:65]
	s_waitcnt vmcnt(0) lgkmcnt(0)
	s_barrier
	v_mfma_f32_16x16x32_bf16 v[54:57], v[144:147], v[160:163], v[54:57]
	ds_read_b128 v[90:93], v142 offset:16384
	s_add_u32 m0, s13, 0x8000
	v_lshl_add_u64 v[176:177], v[80:81], 0, s[14:15]
	global_load_lds_dwordx4 v[176:177], off
	v_mfma_f32_16x16x32_bf16 v[50:53], v[148:151], v[160:163], v[50:53]
	ds_read_b128 v[94:97], v142 offset:18432
	s_add_u32 m0, s13, 0x9000
	v_lshl_add_u64 v[178:179], v[78:79], 0, s[14:15]
	global_load_lds_dwordx4 v[178:179], off
	v_mfma_f32_16x16x32_bf16 v[46:49], v[152:155], v[160:163], v[46:49]
	ds_read_b128 v[98:101], v142 offset:20480
	s_add_u32 m0, s13, 0xa000
	v_lshl_add_u64 v[176:177], v[76:77], 0, s[14:15]
	global_load_lds_dwordx4 v[176:177], off
	v_mfma_f32_16x16x32_bf16 v[42:45], v[156:159], v[160:163], v[42:45]
	ds_read_b128 v[102:105], v142 offset:22528
	s_add_u32 m0, s13, 0xb000
	v_lshl_add_u64 v[178:179], v[74:75], 0, s[14:15]
	global_load_lds_dwordx4 v[178:179], off
	v_mfma_f32_16x16x32_bf16 v[38:41], v[144:147], v[164:167], v[38:41]
	ds_read_b128 v[106:109], v141
	s_add_u32 m0, s13, 0xc000
	v_lshl_add_u64 v[176:177], v[72:73], 0, s[14:15]
	global_load_lds_dwordx4 v[176:177], off
	v_mfma_f32_16x16x32_bf16 v[34:37], v[148:151], v[164:167], v[34:37]
	ds_read_b128 v[110:113], v141 offset:2048
	s_add_u32 m0, s13, 0xd000
	v_lshl_add_u64 v[178:179], v[70:71], 0, s[14:15]
	global_load_lds_dwordx4 v[178:179], off
	v_mfma_f32_16x16x32_bf16 v[30:33], v[152:155], v[164:167], v[30:33]
	ds_read_b128 v[114:117], v141 offset:4096
	s_add_u32 m0, s13, 0xe000
	v_lshl_add_u64 v[176:177], v[68:69], 0, s[14:15]
	global_load_lds_dwordx4 v[176:177], off
	v_mfma_f32_16x16x32_bf16 v[26:29], v[156:159], v[164:167], v[26:29]
	ds_read_b128 v[118:121], v141 offset:6144
	s_add_u32 m0, s13, 0xf000
	v_lshl_add_u64 v[178:179], v[66:67], 0, s[14:15]
	global_load_lds_dwordx4 v[178:179], off
	v_mfma_f32_16x16x32_bf16 v[22:25], v[144:147], v[168:171], v[22:25]
	v_mfma_f32_16x16x32_bf16 v[18:21], v[148:151], v[168:171], v[18:21]
	v_mfma_f32_16x16x32_bf16 v[14:17], v[152:155], v[168:171], v[14:17]
	v_mfma_f32_16x16x32_bf16 v[10:13], v[156:159], v[168:171], v[10:13]
	v_mfma_f32_16x16x32_bf16 v[6:9], v[144:147], v[172:175], v[6:9]
	v_mfma_f32_16x16x32_bf16 v[2:5], v[148:151], v[172:175], v[2:5]
	v_mfma_f32_16x16x32_bf16 v[58:61], v[152:155], v[172:175], v[58:61]
	v_mfma_f32_16x16x32_bf16 v[62:65], v[156:159], v[172:175], v[62:65]
	s_add_u32 s14, s14, 0x80
	s_addc_u32 s15, s15, 0
	s_sub_u32 s16, s16, 1
	s_cmp_lg_u32 s16, 0
	s_cbranch_scc1 .Lgp_i28_loop
	s_waitcnt lgkmcnt(0)
	v_mfma_f32_16x16x32_bf16 v[54:57], v[90:93], v[106:109], v[54:57]
	ds_read_b128 v[144:147], v142 offset:17408
	v_mfma_f32_16x16x32_bf16 v[50:53], v[94:97], v[106:109], v[50:53]
	ds_read_b128 v[148:151], v142 offset:19456
	v_mfma_f32_16x16x32_bf16 v[46:49], v[98:101], v[106:109], v[46:49]
	ds_read_b128 v[152:155], v142 offset:21504
	v_mfma_f32_16x16x32_bf16 v[42:45], v[102:105], v[106:109], v[42:45]
	ds_read_b128 v[156:159], v142 offset:23552
	v_mfma_f32_16x16x32_bf16 v[38:41], v[90:93], v[110:113], v[38:41]
	ds_read_b128 v[160:163], v141 offset:1024
	v_mfma_f32_16x16x32_bf16 v[34:37], v[94:97], v[110:113], v[34:37]
	ds_read_b128 v[164:167], v141 offset:3072
	v_mfma_f32_16x16x32_bf16 v[30:33], v[98:101], v[110:113], v[30:33]
	ds_read_b128 v[168:171], v141 offset:5120
	v_mfma_f32_16x16x32_bf16 v[26:29], v[102:105], v[110:113], v[26:29]
	ds_read_b128 v[172:175], v141 offset:7168
	v_mfma_f32_16x16x32_bf16 v[22:25], v[90:93], v[114:117], v[22:25]
	v_mfma_f32_16x16x32_bf16 v[18:21], v[94:97], v[114:117], v[18:21]
	v_mfma_f32_16x16x32_bf16 v[14:17], v[98:101], v[114:117], v[14:17]
	v_mfma_f32_16x16x32_bf16 v[10:13], v[102:105], v[114:117], v[10:13]
	v_mfma_f32_16x16x32_bf16 v[6:9], v[90:93], v[118:121], v[6:9]
	v_mfma_f32_16x16x32_bf16 v[2:5], v[94:97], v[118:121], v[2:5]
	v_mfma_f32_16x16x32_bf16 v[58:61], v[98:101], v[118:121], v[58:61]
	v_mfma_f32_16x16x32_bf16 v[62:65], v[102:105], v[118:121], v[62:65]
	s_waitcnt vmcnt(0) lgkmcnt(0)
	s_barrier
	v_mfma_f32_16x16x32_bf16 v[54:57], v[144:147], v[160:163], v[54:57]
	v_mfma_f32_16x16x32_bf16 v[50:53], v[148:151], v[160:163], v[50:53]
	v_mfma_f32_16x16x32_bf16 v[46:49], v[152:155], v[160:163], v[46:49]
	v_mfma_f32_16x16x32_bf16 v[42:45], v[156:159], v[160:163], v[42:45]
	v_mfma_f32_16x16x32_bf16 v[38:41], v[144:147], v[164:167], v[38:41]
	v_mfma_f32_16x16x32_bf16 v[34:37], v[148:151], v[164:167], v[34:37]
	v_mfma_f32_16x16x32_bf16 v[30:33], v[152:155], v[164:167], v[30:33]
	v_mfma_f32_16x16x32_bf16 v[26:29], v[156:159], v[164:167], v[26:29]
	v_mfma_f32_16x16x32_bf16 v[22:25], v[144:147], v[168:171], v[22:25]
	v_mfma_f32_16x16x32_bf16 v[18:21], v[148:151], v[168:171], v[18:21]
	v_mfma_f32_16x16x32_bf16 v[14:17], v[152:155], v[168:171], v[14:17]
	v_mfma_f32_16x16x32_bf16 v[10:13], v[156:159], v[168:171], v[10:13]
	v_mfma_f32_16x16x32_bf16 v[6:9], v[144:147], v[172:175], v[6:9]
	v_mfma_f32_16x16x32_bf16 v[2:5], v[148:151], v[172:175], v[2:5]
	v_mfma_f32_16x16x32_bf16 v[58:61], v[152:155], v[172:175], v[58:61]
	v_mfma_f32_16x16x32_bf16 v[62:65], v[156:159], v[172:175], v[62:65]
	v_add3_u32 v0, 0, v83, v89
	ds_read_b128 v[74:77], v0 offset:49152
	ds_read_b128 v[78:81], v0 offset:51200
	ds_read_b128 v[90:93], v0 offset:53248
	ds_read_b128 v[94:97], v0 offset:55296
	s_add_i32 s11, s12, 0xffffe000
	s_lshr_b32 s11, s11, 12
	s_add_i32 s11, s11, 1
	v_add3_u32 v126, 0, v83, v87
	v_add3_u32 v131, 0, v84, v85
	s_cmp_gt_i32 s22, 63
	ds_read_b128 v[66:69], v126 offset:32768
	ds_read_b128 v[70:73], v131 offset:32768
	v_add3_u32 v134, 0, v84, v88
	v_add3_u32 v135, 0, v84, v86
	s_cselect_b32 s11, s11, 0
	s_mul_i32 s13, s62, 3
	ds_read_b128 v[98:101], v134 offset:32768
	ds_read_b128 v[82:85], v135 offset:32768
	s_add_i32 s11, s11, s13
	s_mul_i32 s14, s11, 0x1800
	s_ashr_i32 s15, s14, 31
	s_lshl_b64 s[14:15], s[14:15], 2
	s_waitcnt lgkmcnt(3)
	v_mfma_f32_16x16x32_bf16 v[86:89], v[74:77], v[66:69], v[54:57]
	s_add_u32 s11, s4, s14
	s_addc_u32 s13, s5, s15
	s_add_u32 s14, s11, 0x5000
	v_mfma_f32_16x16x32_bf16 v[102:105], v[78:81], v[66:69], v[50:53]
	s_addc_u32 s15, s13, 0
	s_add_i32 s21, s21, s83
	s_cmpk_gt_i32 s21, 0x7f
	ds_read_b128 v[50:53], v0 offset:50176
	v_mfma_f32_16x16x32_bf16 v[106:109], v[90:93], v[66:69], v[46:49]
	v_mfma_f32_16x16x32_bf16 v[110:113], v[94:97], v[66:69], v[42:45]
	s_nop 2
	ds_read_b128 v[42:45], v0 offset:52224
	s_waitcnt lgkmcnt(4)
	v_mfma_f32_16x16x32_bf16 v[114:117], v[74:77], v[70:73], v[38:41]
	v_mfma_f32_16x16x32_bf16 v[118:121], v[78:81], v[70:73], v[34:37]
	s_nop 2
	ds_read_b128 v[34:37], v0 offset:54272
	v_mfma_f32_16x16x32_bf16 v[122:125], v[90:93], v[70:73], v[30:33]
	v_mfma_f32_16x16x32_bf16 v[66:69], v[94:97], v[70:73], v[26:29]
	s_nop 2
	ds_read_b128 v[26:29], v0 offset:56320
	v_mov_b32_e32 v0, v133
	s_waitcnt lgkmcnt(5)
	v_mfma_f32_16x16x32_bf16 v[54:57], v[74:77], v[98:101], v[22:25]
	v_mfma_f32_16x16x32_bf16 v[46:49], v[78:81], v[98:101], v[18:21]
	ds_read_b128 v[126:129], v126 offset:33792
	v_mfma_f32_16x16x32_bf16 v[38:41], v[90:93], v[98:101], v[14:17]
	v_mfma_f32_16x16x32_bf16 v[22:25], v[94:97], v[98:101], v[10:13]
	ds_read_b128 v[70:73], v131 offset:33792
	s_waitcnt lgkmcnt(6)
	v_mfma_f32_16x16x32_bf16 v[18:21], v[74:77], v[82:85], v[6:9]
	v_mfma_f32_16x16x32_bf16 v[14:17], v[78:81], v[82:85], v[2:5]
	ds_read_b128 v[30:33], v134 offset:33792
	v_mfma_f32_16x16x32_bf16 v[10:13], v[90:93], v[82:85], v[58:61]
	v_mfma_f32_16x16x32_bf16 v[2:5], v[94:97], v[82:85], v[62:65]
	ds_read_b128 v[6:9], v135 offset:33792
	s_waitcnt vmcnt(0)
	s_waitcnt lgkmcnt(0)
	s_barrier
	v_mfma_f32_16x16x32_bf16 v[82:85], v[50:53], v[126:129], v[86:89]
	v_ashrrev_i32_e32 v58, 1, v0
	v_and_b32_e32 v58, 0xffffffc0, v58
	v_add_u32_e32 v58, s12, v58
	s_load_dwordx2 s[12:13], s[0:1], 0x128
	v_and_or_b32 v58, v0, 15, v58
	v_and_b32_e32 v59, 64, v0
	v_lshrrev_b32_e32 v0, 2, v0
	v_and_b32_e32 v0, 12, v0
	v_or3_b32 v94, v59, v0, s10
	v_ashrrev_i32_e32 v59, 31, v58
	v_ashrrev_i32_e32 v95, 31, v94
	v_lshlrev_b64 v[60:61], 12, v[58:59]
	s_waitcnt lgkmcnt(0)
	v_lshl_add_u64 v[60:61], s[12:13], 0, v[60:61]
	v_lshlrev_b64 v[64:65], 2, v[94:95]
	v_lshl_add_u64 v[96:97], v[60:61], 0, v[64:65]
	v_lshl_add_u64 v[60:61], s[14:15], 0, v[64:65]
	global_load_dwordx4 v[74:77], v[60:61], off
	global_load_dwordx4 v[78:81], v[96:97], off
	v_or_b32_e32 v62, 16, v94
	v_ashrrev_i32_e32 v63, 31, v62
	v_lshl_add_u64 v[62:63], v[62:63], 2, s[14:15]
	global_load_dwordx4 v[86:89], v[96:97], off offset:64
	global_load_dwordx4 v[90:93], v[96:97], off offset:128
	v_mfma_f32_16x16x32_bf16 v[66:69], v[26:29], v[70:73], v[66:69]
	s_waitcnt vmcnt(2)
	v_pk_fma_f32 v[74:75], v[82:83], v[74:75], v[78:79]
	v_pk_fma_f32 v[76:77], v[84:85], v[76:77], v[80:81]
	global_store_dwordx4 v[96:97], v[74:77], off
	global_load_dwordx4 v[76:79], v[62:63], off
	v_mfma_f32_16x16x32_bf16 v[80:83], v[42:45], v[126:129], v[102:105]
	v_or_b32_e32 v74, 32, v94
	v_ashrrev_i32_e32 v75, 31, v74
	v_lshl_add_u64 v[74:75], v[74:75], 2, s[14:15]
	v_mfma_f32_16x16x32_bf16 v[54:57], v[50:53], v[30:33], v[54:57]
	v_mfma_f32_16x16x32_bf16 v[46:49], v[42:45], v[30:33], v[46:49]
	s_waitcnt vmcnt(0)
	s_nop 1
	v_pk_fma_f32 v[76:77], v[80:81], v[76:77], v[86:87]
	v_pk_fma_f32 v[78:79], v[82:83], v[78:79], v[88:89]
	global_store_dwordx4 v[96:97], v[76:79], off offset:64
	global_load_dwordx4 v[78:81], v[74:75], off
	v_mfma_f32_16x16x32_bf16 v[82:85], v[34:37], v[126:129], v[106:109]
	v_or_b32_e32 v76, 48, v94
	v_ashrrev_i32_e32 v77, 31, v76
	v_lshl_add_u64 v[76:77], v[76:77], 2, s[14:15]
	global_load_dwordx4 v[86:89], v[96:97], off offset:192
	v_mfma_f32_16x16x32_bf16 v[38:41], v[34:37], v[30:33], v[38:41]
	s_waitcnt vmcnt(1)
	s_nop 1
	v_pk_fma_f32 v[78:79], v[82:83], v[78:79], v[90:91]
	v_pk_fma_f32 v[80:81], v[84:85], v[80:81], v[92:93]
	global_store_dwordx4 v[96:97], v[78:81], off offset:128
	global_load_dwordx4 v[78:81], v[76:77], off
	v_or_b32_e32 v82, 16, v58
	v_ashrrev_i32_e32 v83, 31, v82
	v_lshlrev_b64 v[82:83], 12, v[82:83]
	v_lshl_add_u64 v[90:91], s[12:13], 0, v[82:83]
	v_mfma_f32_16x16x32_bf16 v[82:85], v[26:29], v[126:129], v[110:113]
	v_lshl_add_u64 v[94:95], v[90:91], 0, v[64:65]
	global_load_dwordx4 v[90:93], v[94:95], off
	v_mfma_f32_16x16x32_bf16 v[22:25], v[26:29], v[30:33], v[22:25]
	v_mfma_f32_16x16x32_bf16 v[18:21], v[50:53], v[6:9], v[18:21]
	s_waitcnt vmcnt(1)
	s_nop 2
	v_pk_fma_f32 v[78:79], v[82:83], v[78:79], v[86:87]
	v_pk_fma_f32 v[80:81], v[84:85], v[80:81], v[88:89]
	global_store_dwordx4 v[96:97], v[78:81], off offset:192
	global_load_dwordx4 v[78:81], v[60:61], off
	v_mfma_f32_16x16x32_bf16 v[82:85], v[50:53], v[70:73], v[114:117]
	global_load_dwordx4 v[86:89], v[94:95], off offset:64
	v_mfma_f32_16x16x32_bf16 v[14:17], v[42:45], v[6:9], v[14:17]
	v_mfma_f32_16x16x32_bf16 v[10:13], v[34:37], v[6:9], v[10:13]
	s_waitcnt vmcnt(1)
	s_nop 3
	v_pk_fma_f32 v[78:79], v[82:83], v[78:79], v[90:91]
	v_pk_fma_f32 v[80:81], v[84:85], v[80:81], v[92:93]
	global_store_dwordx4 v[94:95], v[78:81], off
	global_load_dwordx4 v[78:81], v[62:63], off
	v_mfma_f32_16x16x32_bf16 v[82:85], v[42:45], v[70:73], v[118:121]
	global_load_dwordx4 v[90:93], v[94:95], off offset:128
	v_mfma_f32_16x16x32_bf16 v[2:5], v[26:29], v[6:9], v[2:5]
	s_waitcnt vmcnt(1)
	s_nop 4
	v_pk_fma_f32 v[78:79], v[82:83], v[78:79], v[86:87]
	v_pk_fma_f32 v[80:81], v[84:85], v[80:81], v[88:89]
	global_store_dwordx4 v[94:95], v[78:81], off offset:64
	global_load_dwordx4 v[78:81], v[74:75], off
	v_mfma_f32_16x16x32_bf16 v[82:85], v[34:37], v[70:73], v[122:125]
	global_load_dwordx4 v[86:89], v[94:95], off offset:192
	s_waitcnt vmcnt(1)
	s_nop 5
	v_pk_fma_f32 v[78:79], v[82:83], v[78:79], v[90:91]
	v_pk_fma_f32 v[80:81], v[84:85], v[80:81], v[92:93]
	global_store_dwordx4 v[94:95], v[78:81], off offset:128
	global_load_dwordx4 v[78:81], v[76:77], off
	v_or_b32_e32 v82, 32, v58
	v_ashrrev_i32_e32 v83, 31, v82
	v_lshlrev_b64 v[82:83], 12, v[82:83]
	v_lshl_add_u64 v[82:83], s[12:13], 0, v[82:83]
	v_lshl_add_u64 v[82:83], v[82:83], 0, v[64:65]
	global_load_dwordx4 v[70:73], v[82:83], off
	s_waitcnt vmcnt(1)
	v_pk_fma_f32 v[66:67], v[66:67], v[78:79], v[86:87]
	v_pk_fma_f32 v[68:69], v[68:69], v[80:81], v[88:89]
	global_store_dwordx4 v[94:95], v[66:69], off offset:192
	global_load_dwordx4 v[66:69], v[60:61], off
	s_waitcnt vmcnt(0)
	v_pk_fma_f32 v[54:55], v[54:55], v[66:67], v[70:71]
	v_pk_fma_f32 v[56:57], v[56:57], v[68:69], v[72:73]
	global_store_dwordx4 v[82:83], v[54:57], off
	global_load_dwordx4 v[78:81], v[82:83], off offset:64
	global_load_dwordx4 v[66:69], v[82:83], off offset:128
	s_nop 0
	global_load_dwordx4 v[54:57], v[62:63], off
	s_waitcnt vmcnt(0)
	v_pk_fma_f32 v[46:47], v[46:47], v[54:55], v[78:79]
	v_pk_fma_f32 v[48:49], v[48:49], v[56:57], v[80:81]
	global_store_dwordx4 v[82:83], v[46:49], off offset:64
	global_load_dwordx4 v[46:49], v[74:75], off
	s_waitcnt vmcnt(0)
	v_pk_fma_f32 v[38:39], v[38:39], v[46:47], v[66:67]
	v_pk_fma_f32 v[40:41], v[40:41], v[48:49], v[68:69]
	global_store_dwordx4 v[82:83], v[38:41], off offset:128
	global_load_dwordx4 v[54:57], v[82:83], off offset:192
	v_or_b32_e32 v46, 48, v58
	global_load_dwordx4 v[38:41], v[76:77], off
	v_ashrrev_i32_e32 v47, 31, v46
	v_lshlrev_b64 v[46:47], 12, v[46:47]
	v_lshl_add_u64 v[46:47], s[12:13], 0, v[46:47]
	v_lshl_add_u64 v[46:47], v[46:47], 0, v[64:65]
	global_load_dwordx4 v[30:33], v[46:47], off
	s_waitcnt vmcnt(1)
	v_pk_fma_f32 v[22:23], v[22:23], v[38:39], v[54:55]
	v_pk_fma_f32 v[24:25], v[24:25], v[40:41], v[56:57]
	global_store_dwordx4 v[82:83], v[22:25], off offset:192
	global_load_dwordx4 v[22:25], v[60:61], off
	s_waitcnt vmcnt(0)
	v_pk_fma_f32 v[18:19], v[18:19], v[22:23], v[30:31]
	v_pk_fma_f32 v[20:21], v[20:21], v[24:25], v[32:33]
	global_store_dwordx4 v[46:47], v[18:21], off
	global_load_dwordx4 v[38:41], v[46:47], off offset:64
	global_load_dwordx4 v[22:25], v[46:47], off offset:128
	s_nop 0
	global_load_dwordx4 v[18:21], v[62:63], off
	s_waitcnt vmcnt(0)
	v_pk_fma_f32 v[14:15], v[14:15], v[18:19], v[38:39]
	v_pk_fma_f32 v[16:17], v[16:17], v[20:21], v[40:41]
	global_store_dwordx4 v[46:47], v[14:17], off offset:64
	global_load_dwordx4 v[14:17], v[74:75], off
	s_waitcnt vmcnt(0)
	v_pk_fma_f32 v[10:11], v[10:11], v[14:15], v[22:23]
	v_pk_fma_f32 v[12:13], v[12:13], v[16:17], v[24:25]
	global_store_dwordx4 v[46:47], v[10:13], off offset:128
	global_load_dwordx4 v[18:21], v[46:47], off offset:192
	s_nop 0
	global_load_dwordx4 v[10:13], v[76:77], off
	s_waitcnt vmcnt(0)
	v_pk_fma_f32 v[2:3], v[2:3], v[10:11], v[18:19]
	v_pk_fma_f32 v[4:5], v[4:5], v[12:13], v[20:21]
	global_store_dwordx4 v[46:47], v[2:5], off offset:192
	s_cbranch_scc0 .LBB0_27

.LBB0_42:
	s_ashr_i32 s10, s21, 31
	s_lshr_b32 s10, s10, 26
	s_add_i32 s10, s21, s10
	s_ashr_i32 s11, s10, 6
	s_lshl_b32 s11, s11, 3
	s_or_b32 s11, s11, s65
	s_ashr_i32 s12, s11, 31
	s_lshr_b32 s12, s12, 30
	s_add_i32 s12, s11, s12
	s_and_b32 s10, s10, 0xffc0
	s_and_b32 s13, s12, 0x3ffffc
	s_sub_i32 s10, s21, s10
	s_sub_i32 s11, s11, s13
	s_bfe_i32 s13, s10, 0x80000
	s_bfe_u32 s13, s13, 0x3000c
	s_add_i32 s13, s10, s13
	s_bfe_i32 s14, s13, 0x80000
	s_sext_i32_i16 s14, s14
	s_and_b32 s13, s13, 0xf8
	s_sub_i32 s10, s10, s13
	s_lshl_b32 s12, s12, 8
	s_lshl_b32 s13, s14, 4
	s_and_b32 s12, s12, 0xfffffc00
	s_and_b32 s13, s13, 0xffffff80
	s_waitcnt vmcnt(9)
	v_mov_b32_e32 v26, v133
	s_sext_i32_i8 s10, s10
	s_add_i32 s12, s12, s13
	s_lshl_b32 s11, s11, 10
	v_lshlrev_b32_e32 v16, 4, v26
	v_and_b32_e32 v0, 32, v26
	s_lshl_b32 s10, s10, 7
	s_ashr_i32 s13, s12, 31
	v_bitop3_b32 v0, v16, v0, 48 bitop3:0x6c
	s_add_i32 s10, s11, s10
	s_lshl_b64 s[16:17], s[12:13], 11
	v_lshrrev_b32_e32 v17, 2, v26
	v_lshrrev_b32_e32 v2, 1, v26
	v_lshrrev_b32_e32 v0, 1, v0
	v_ashrrev_i32_e32 v4, 3, v26
	s_add_u32 s22, s3, s16
	v_and_b32_e32 v27, 0xfffffc00, v16
	v_and_or_b32 v0, v2, 32, v0
	v_bfi_b32 v4, -16, v4, v17
	s_addc_u32 s23, s18, s17
	s_ashr_i32 s11, s10, 31
	v_lshlrev_b32_e32 v0, 1, v0
	v_ashrrev_i32_e32 v5, 31, v4
	v_add_u32_e32 v8, 0x1000, v16
	v_add_u32_e32 v82, 0, v27
	s_lshl_b64 s[14:15], s[10:11], 11
	v_lshl_add_u64 v[2:3], s[22:23], 0, v[0:1]
	v_lshlrev_b64 v[4:5], 11, v[4:5]
	v_ashrrev_i32_e32 v8, 7, v8
	v_add_u32_e32 v12, 0x2000, v16
	v_readfirstlane_b32 s11, v82
	v_lshl_add_u64 v[6:7], v[2:3], 0, v[4:5]
	v_bfi_b32 v8, -16, v8, v17
	v_ashrrev_i32_e32 v12, 7, v12
	v_add_u32_e32 v16, 0x3000, v16
	s_mov_b32 m0, s11
	v_ashrrev_i32_e32 v9, 31, v8
	v_bfi_b32 v12, -16, v12, v17
	v_ashrrev_i32_e32 v16, 7, v16
	s_barrier
	global_load_lds_dwordx4 v[6:7], off
	v_add_u32_e32 v6, 0x1000, v82
	v_lshlrev_b64 v[8:9], 11, v[8:9]
	v_ashrrev_i32_e32 v13, 31, v12
	v_bfi_b32 v16, -16, v16, v17
	v_readfirstlane_b32 s11, v6
	v_add_u32_e32 v6, 0x2000, v82
	v_lshl_add_u64 v[10:11], v[2:3], 0, v[8:9]
	v_lshlrev_b64 v[12:13], 11, v[12:13]
	v_ashrrev_i32_e32 v17, 31, v16
	s_mov_b32 m0, s11
	v_readfirstlane_b32 s11, v6
	v_add_u32_e32 v6, 0x3000, v82
	v_lshl_add_u64 v[14:15], v[2:3], 0, v[12:13]
	v_lshlrev_b64 v[16:17], 11, v[16:17]
	global_load_lds_dwordx4 v[10:11], off
	s_mov_b32 m0, s11
	v_readfirstlane_b32 s11, v6
	s_add_u32 s24, s19, s14
	v_lshl_add_u64 v[2:3], v[2:3], 0, v[16:17]
	global_load_lds_dwordx4 v[14:15], off
	s_mov_b32 m0, s11
	s_addc_u32 s25, s20, s15
	global_load_lds_dwordx4 v[2:3], off
	v_add_u32_e32 v2, 0x4000, v82
	v_lshl_add_u64 v[18:19], s[24:25], 0, v[0:1]
	v_readfirstlane_b32 s11, v2
	v_add_u32_e32 v2, 0x5000, v82
	v_lshl_add_u64 v[20:21], v[18:19], 0, v[4:5]
	s_mov_b32 m0, s11
	v_readfirstlane_b32 s11, v2
	v_add_u32_e32 v2, 0x6000, v82
	v_lshl_add_u64 v[22:23], v[18:19], 0, v[8:9]
	global_load_lds_dwordx4 v[20:21], off
	s_mov_b32 m0, s11
	v_readfirstlane_b32 s11, v2
	v_add_u32_e32 v2, 0x7000, v82
	v_lshl_add_u64 v[24:25], v[18:19], 0, v[12:13]
	global_load_lds_dwordx4 v[22:23], off
	s_mov_b32 m0, s11
	v_readfirstlane_b32 s11, v2
	v_lshl_add_u64 v[18:19], v[18:19], 0, v[16:17]
	global_load_lds_dwordx4 v[24:25], off
	s_mov_b32 m0, s11
	v_and_b32_e32 v2, 15, v26
	global_load_lds_dwordx4 v[18:19], off
	v_lshlrev_b32_e32 v6, 2, v26
	v_and_b32_e32 v3, 48, v26
	v_lshlrev_b32_e32 v2, 6, v2
	v_and_b32_e32 v6, 32, v6
	v_bitop3_b32 v83, v2, v6, v3 bitop3:0x36
	v_lshlrev_b32_e32 v2, 7, v26
	v_and_b32_e32 v89, 0x2000, v2
	v_lshlrev_b32_e32 v2, 6, v26
	v_and_b32_e32 v87, 0xffffe000, v2
	v_and_b32_e32 v2, 0x3c0, v2
	v_bitop3_b32 v84, v2, v6, v3 bitop3:0x36
	v_lshl_add_u64 v[2:3], s[16:17], 0, v[4:5]
	v_or_b32_e32 v2, v2, v0
	v_lshl_add_u64 v[66:67], s[6:7], 0, v[2:3]
	v_lshl_add_u64 v[2:3], s[16:17], 0, v[8:9]
	v_or_b32_e32 v2, v2, v0
	v_lshl_add_u64 v[68:69], s[6:7], 0, v[2:3]
	v_lshl_add_u64 v[2:3], s[16:17], 0, v[12:13]
	v_or_b32_e32 v2, v2, v0
	v_lshl_add_u64 v[70:71], s[6:7], 0, v[2:3]
	v_lshl_add_u64 v[2:3], s[16:17], 0, v[16:17]
	v_or_b32_e32 v2, v2, v0
	v_lshl_add_u64 v[72:73], s[6:7], 0, v[2:3]
	v_lshl_add_u64 v[2:3], s[14:15], 0, v[4:5]
	v_or_b32_e32 v2, v2, v0
	v_lshl_add_u64 v[74:75], s[8:9], 0, v[2:3]
	v_lshl_add_u64 v[2:3], s[14:15], 0, v[8:9]
	v_or_b32_e32 v2, v2, v0
	v_lshl_add_u64 v[76:77], s[8:9], 0, v[2:3]
	v_lshl_add_u64 v[2:3], s[14:15], 0, v[12:13]
	v_or_b32_e32 v2, v2, v0
	s_waitcnt vmcnt(0)
	v_lshl_add_u64 v[78:79], s[8:9], 0, v[2:3]
	v_lshl_add_u64 v[2:3], s[14:15], 0, v[16:17]
	v_or_b32_e32 v2, v2, v0
	v_mov_b32_e32 v62, 0
	v_or_b32_e32 v85, 0x800, v87
	v_or_b32_e32 v88, 0x1000, v87
	v_or_b32_e32 v86, 0x1800, v87
	v_lshl_add_u64 v[80:81], s[8:9], 0, v[2:3]
	s_mov_b64 s[14:15], 0
	s_mov_b32 s11, 0
	v_mov_b32_e32 v63, v62
	v_mov_b32_e32 v64, v62
	v_mov_b32_e32 v65, v62
	v_mov_b32_e32 v58, v62
	v_mov_b32_e32 v59, v62
	v_mov_b32_e32 v60, v62
	v_mov_b32_e32 v61, v62
	v_mov_b32_e32 v2, v62
	v_mov_b32_e32 v3, v62
	v_mov_b32_e32 v4, v62
	v_mov_b32_e32 v5, v62
	v_mov_b32_e32 v6, v62
	v_mov_b32_e32 v7, v62
	v_mov_b32_e32 v8, v62
	v_mov_b32_e32 v9, v62
	v_mov_b32_e32 v10, v62
	v_mov_b32_e32 v11, v62
	v_mov_b32_e32 v12, v62
	v_mov_b32_e32 v13, v62
	v_mov_b32_e32 v14, v62
	v_mov_b32_e32 v15, v62
	v_mov_b32_e32 v16, v62
	v_mov_b32_e32 v17, v62
	v_mov_b32_e32 v18, v62
	v_mov_b32_e32 v19, v62
	v_mov_b32_e32 v20, v62
	v_mov_b32_e32 v21, v62
	v_mov_b32_e32 v22, v62
	v_mov_b32_e32 v23, v62
	v_mov_b32_e32 v24, v62
	v_mov_b32_e32 v25, v62
	v_mov_b32_e32 v26, v62
	v_mov_b32_e32 v27, v62
	v_mov_b32_e32 v28, v62
	v_mov_b32_e32 v29, v62
	s_waitcnt vmcnt(0)
	v_mov_b32_e32 v30, v62
	v_mov_b32_e32 v31, v62
	v_mov_b32_e32 v32, v62
	v_mov_b32_e32 v33, v62
	v_mov_b32_e32 v34, v62
	v_mov_b32_e32 v35, v62
	v_mov_b32_e32 v36, v62
	v_mov_b32_e32 v37, v62
	v_mov_b32_e32 v38, v62
	v_mov_b32_e32 v39, v62
	v_mov_b32_e32 v40, v62
	v_mov_b32_e32 v41, v62
	v_mov_b32_e32 v42, v62
	v_mov_b32_e32 v43, v62
	v_mov_b32_e32 v44, v62
	v_mov_b32_e32 v45, v62
	v_mov_b32_e32 v46, v62
	v_mov_b32_e32 v47, v62
	v_mov_b32_e32 v48, v62
	v_mov_b32_e32 v49, v62
	v_mov_b32_e32 v50, v62
	v_mov_b32_e32 v51, v62
	v_mov_b32_e32 v52, v62
	v_mov_b32_e32 v53, v62
	v_mov_b32_e32 v54, v62
	v_mov_b32_e32 v55, v62
	v_mov_b32_e32 v56, v62
	v_mov_b32_e32 v57, v62
	s_waitcnt vmcnt(0) lgkmcnt(0)
	s_barrier
	v_readfirstlane_b32 s13, v82
	v_add_u32_e32 v141, v83, v87
	v_add_u32_e32 v142, v83, v89
	ds_read_b128 v[90:93], v142 offset:16384
	ds_read_b128 v[94:97], v142 offset:18432
	ds_read_b128 v[98:101], v142 offset:20480
	ds_read_b128 v[102:105], v142 offset:22528
	ds_read_b128 v[106:109], v141
	ds_read_b128 v[110:113], v141 offset:2048
	ds_read_b128 v[114:117], v141 offset:4096
	ds_read_b128 v[118:121], v141 offset:6144
	s_add_u32 m0, s13, 0x8000
	v_lshl_add_u64 v[176:177], v[66:67], 0, s[14:15]
	global_load_lds_dwordx4 v[176:177], off
	s_add_u32 m0, s13, 0x9000
	v_lshl_add_u64 v[178:179], v[68:69], 0, s[14:15]
	global_load_lds_dwordx4 v[178:179], off
	s_add_u32 m0, s13, 0xa000
	v_lshl_add_u64 v[176:177], v[70:71], 0, s[14:15]
	global_load_lds_dwordx4 v[176:177], off
	s_add_u32 m0, s13, 0xb000
	v_lshl_add_u64 v[178:179], v[72:73], 0, s[14:15]
	global_load_lds_dwordx4 v[178:179], off
	s_add_u32 m0, s13, 0xc000
	v_lshl_add_u64 v[176:177], v[74:75], 0, s[14:15]
	global_load_lds_dwordx4 v[176:177], off
	s_add_u32 m0, s13, 0xd000
	v_lshl_add_u64 v[178:179], v[76:77], 0, s[14:15]
	global_load_lds_dwordx4 v[178:179], off
	s_add_u32 m0, s13, 0xe000
	v_lshl_add_u64 v[176:177], v[78:79], 0, s[14:15]
	global_load_lds_dwordx4 v[176:177], off
	s_add_u32 m0, s13, 0xf000
	v_lshl_add_u64 v[178:179], v[80:81], 0, s[14:15]
	global_load_lds_dwordx4 v[178:179], off
	s_add_u32 s14, s14, 0x80
	s_addc_u32 s15, s15, 0
	s_mov_b32 s16, 7
.Lgp_i43_loop:
	s_waitcnt lgkmcnt(0)
	v_mfma_f32_16x16x32_bf16 v[54:57], v[90:93], v[106:109], v[54:57]
	ds_read_b128 v[144:147], v142 offset:17408
	v_mfma_f32_16x16x32_bf16 v[50:53], v[94:97], v[106:109], v[50:53]
	ds_read_b128 v[148:151], v142 offset:19456
	v_mfma_f32_16x16x32_bf16 v[46:49], v[98:101], v[106:109], v[46:49]
	ds_read_b128 v[152:155], v142 offset:21504
	v_mfma_f32_16x16x32_bf16 v[42:45], v[102:105], v[106:109], v[42:45]
	ds_read_b128 v[156:159], v142 offset:23552
	v_mfma_f32_16x16x32_bf16 v[38:41], v[90:93], v[110:113], v[38:41]
	ds_read_b128 v[160:163], v141 offset:1024
	v_mfma_f32_16x16x32_bf16 v[34:37], v[94:97], v[110:113], v[34:37]
	ds_read_b128 v[164:167], v141 offset:3072
	v_mfma_f32_16x16x32_bf16 v[30:33], v[98:101], v[110:113], v[30:33]
	ds_read_b128 v[168:171], v141 offset:5120
	v_mfma_f32_16x16x32_bf16 v[26:29], v[102:105], v[110:113], v[26:29]
	ds_read_b128 v[172:175], v141 offset:7168
	v_mfma_f32_16x16x32_bf16 v[22:25], v[90:93], v[114:117], v[22:25]
	v_mfma_f32_16x16x32_bf16 v[18:21], v[94:97], v[114:117], v[18:21]
	v_mfma_f32_16x16x32_bf16 v[14:17], v[98:101], v[114:117], v[14:17]
	v_mfma_f32_16x16x32_bf16 v[10:13], v[102:105], v[114:117], v[10:13]
	v_mfma_f32_16x16x32_bf16 v[6:9], v[90:93], v[118:121], v[6:9]
	v_mfma_f32_16x16x32_bf16 v[2:5], v[94:97], v[118:121], v[2:5]
	v_mfma_f32_16x16x32_bf16 v[58:61], v[98:101], v[118:121], v[58:61]
	v_mfma_f32_16x16x32_bf16 v[62:65], v[102:105], v[118:121], v[62:65]
	s_waitcnt vmcnt(0) lgkmcnt(0)
	s_barrier
	v_mfma_f32_16x16x32_bf16 v[54:57], v[144:147], v[160:163], v[54:57]
	ds_read_b128 v[90:93], v142 offset:49152
	s_add_u32 m0, s13, 0x0
	v_lshl_add_u64 v[176:177], v[66:67], 0, s[14:15]
	global_load_lds_dwordx4 v[176:177], off
	v_mfma_f32_16x16x32_bf16 v[50:53], v[148:151], v[160:163], v[50:53]
	ds_read_b128 v[94:97], v142 offset:51200
	s_add_u32 m0, s13, 0x1000
	v_lshl_add_u64 v[178:179], v[68:69], 0, s[14:15]
	global_load_lds_dwordx4 v[178:179], off
	v_mfma_f32_16x16x32_bf16 v[46:49], v[152:155], v[160:163], v[46:49]
	ds_read_b128 v[98:101], v142 offset:53248
	s_add_u32 m0, s13, 0x2000
	v_lshl_add_u64 v[176:177], v[70:71], 0, s[14:15]
	global_load_lds_dwordx4 v[176:177], off
	v_mfma_f32_16x16x32_bf16 v[42:45], v[156:159], v[160:163], v[42:45]
	ds_read_b128 v[102:105], v142 offset:55296
	s_add_u32 m0, s13, 0x3000
	v_lshl_add_u64 v[178:179], v[72:73], 0, s[14:15]
	global_load_lds_dwordx4 v[178:179], off
	v_mfma_f32_16x16x32_bf16 v[38:41], v[144:147], v[164:167], v[38:41]
	ds_read_b128 v[106:109], v141 offset:32768
	s_add_u32 m0, s13, 0x4000
	v_lshl_add_u64 v[176:177], v[74:75], 0, s[14:15]
	global_load_lds_dwordx4 v[176:177], off
	v_mfma_f32_16x16x32_bf16 v[34:37], v[148:151], v[164:167], v[34:37]
	ds_read_b128 v[110:113], v141 offset:34816
	s_add_u32 m0, s13, 0x5000
	v_lshl_add_u64 v[178:179], v[76:77], 0, s[14:15]
	global_load_lds_dwordx4 v[178:179], off
	v_mfma_f32_16x16x32_bf16 v[30:33], v[152:155], v[164:167], v[30:33]
	ds_read_b128 v[114:117], v141 offset:36864
	s_add_u32 m0, s13, 0x6000
	v_lshl_add_u64 v[176:177], v[78:79], 0, s[14:15]
	global_load_lds_dwordx4 v[176:177], off
	v_mfma_f32_16x16x32_bf16 v[26:29], v[156:159], v[164:167], v[26:29]
	ds_read_b128 v[118:121], v141 offset:38912
	s_add_u32 m0, s13, 0x7000
	v_lshl_add_u64 v[178:179], v[80:81], 0, s[14:15]
	global_load_lds_dwordx4 v[178:179], off
	v_mfma_f32_16x16x32_bf16 v[22:25], v[144:147], v[168:171], v[22:25]
	v_mfma_f32_16x16x32_bf16 v[18:21], v[148:151], v[168:171], v[18:21]
	v_mfma_f32_16x16x32_bf16 v[14:17], v[152:155], v[168:171], v[14:17]
	v_mfma_f32_16x16x32_bf16 v[10:13], v[156:159], v[168:171], v[10:13]
	v_mfma_f32_16x16x32_bf16 v[6:9], v[144:147], v[172:175], v[6:9]
	v_mfma_f32_16x16x32_bf16 v[2:5], v[148:151], v[172:175], v[2:5]
	v_mfma_f32_16x16x32_bf16 v[58:61], v[152:155], v[172:175], v[58:61]
	v_mfma_f32_16x16x32_bf16 v[62:65], v[156:159], v[172:175], v[62:65]
	s_add_u32 s14, s14, 0x80
	s_addc_u32 s15, s15, 0
	s_waitcnt lgkmcnt(0)
	v_mfma_f32_16x16x32_bf16 v[54:57], v[90:93], v[106:109], v[54:57]
	ds_read_b128 v[144:147], v142 offset:50176
	v_mfma_f32_16x16x32_bf16 v[50:53], v[94:97], v[106:109], v[50:53]
	ds_read_b128 v[148:151], v142 offset:52224
	v_mfma_f32_16x16x32_bf16 v[46:49], v[98:101], v[106:109], v[46:49]
	ds_read_b128 v[152:155], v142 offset:54272
	v_mfma_f32_16x16x32_bf16 v[42:45], v[102:105], v[106:109], v[42:45]
	ds_read_b128 v[156:159], v142 offset:56320
	v_mfma_f32_16x16x32_bf16 v[38:41], v[90:93], v[110:113], v[38:41]
	ds_read_b128 v[160:163], v141 offset:33792
	v_mfma_f32_16x16x32_bf16 v[34:37], v[94:97], v[110:113], v[34:37]
	ds_read_b128 v[164:167], v141 offset:35840
	v_mfma_f32_16x16x32_bf16 v[30:33], v[98:101], v[110:113], v[30:33]
	ds_read_b128 v[168:171], v141 offset:37888
	v_mfma_f32_16x16x32_bf16 v[26:29], v[102:105], v[110:113], v[26:29]
	ds_read_b128 v[172:175], v141 offset:39936
	v_mfma_f32_16x16x32_bf16 v[22:25], v[90:93], v[114:117], v[22:25]
	v_mfma_f32_16x16x32_bf16 v[18:21], v[94:97], v[114:117], v[18:21]
	v_mfma_f32_16x16x32_bf16 v[14:17], v[98:101], v[114:117], v[14:17]
	v_mfma_f32_16x16x32_bf16 v[10:13], v[102:105], v[114:117], v[10:13]
	v_mfma_f32_16x16x32_bf16 v[6:9], v[90:93], v[118:121], v[6:9]
	v_mfma_f32_16x16x32_bf16 v[2:5], v[94:97], v[118:121], v[2:5]
	v_mfma_f32_16x16x32_bf16 v[58:61], v[98:101], v[118:121], v[58:61]
	v_mfma_f32_16x16x32_bf16 v[62:65], v[102:105], v[118:121], v[62:65]
	s_waitcnt vmcnt(0) lgkmcnt(0)
	s_barrier
	v_mfma_f32_16x16x32_bf16 v[54:57], v[144:147], v[160:163], v[54:57]
	ds_read_b128 v[90:93], v142 offset:16384
	s_add_u32 m0, s13, 0x8000
	v_lshl_add_u64 v[176:177], v[66:67], 0, s[14:15]
	global_load_lds_dwordx4 v[176:177], off
	v_mfma_f32_16x16x32_bf16 v[50:53], v[148:151], v[160:163], v[50:53]
	ds_read_b128 v[94:97], v142 offset:18432
	s_add_u32 m0, s13, 0x9000
	v_lshl_add_u64 v[178:179], v[68:69], 0, s[14:15]
	global_load_lds_dwordx4 v[178:179], off
	v_mfma_f32_16x16x32_bf16 v[46:49], v[152:155], v[160:163], v[46:49]
	ds_read_b128 v[98:101], v142 offset:20480
	s_add_u32 m0, s13, 0xa000
	v_lshl_add_u64 v[176:177], v[70:71], 0, s[14:15]
	global_load_lds_dwordx4 v[176:177], off
	v_mfma_f32_16x16x32_bf16 v[42:45], v[156:159], v[160:163], v[42:45]
	ds_read_b128 v[102:105], v142 offset:22528
	s_add_u32 m0, s13, 0xb000
	v_lshl_add_u64 v[178:179], v[72:73], 0, s[14:15]
	global_load_lds_dwordx4 v[178:179], off
	v_mfma_f32_16x16x32_bf16 v[38:41], v[144:147], v[164:167], v[38:41]
	ds_read_b128 v[106:109], v141
	s_add_u32 m0, s13, 0xc000
	v_lshl_add_u64 v[176:177], v[74:75], 0, s[14:15]
	global_load_lds_dwordx4 v[176:177], off
	v_mfma_f32_16x16x32_bf16 v[34:37], v[148:151], v[164:167], v[34:37]
	ds_read_b128 v[110:113], v141 offset:2048
	s_add_u32 m0, s13, 0xd000
	v_lshl_add_u64 v[178:179], v[76:77], 0, s[14:15]
	global_load_lds_dwordx4 v[178:179], off
	v_mfma_f32_16x16x32_bf16 v[30:33], v[152:155], v[164:167], v[30:33]
	ds_read_b128 v[114:117], v141 offset:4096
	s_add_u32 m0, s13, 0xe000
	v_lshl_add_u64 v[176:177], v[78:79], 0, s[14:15]
	global_load_lds_dwordx4 v[176:177], off
	v_mfma_f32_16x16x32_bf16 v[26:29], v[156:159], v[164:167], v[26:29]
	ds_read_b128 v[118:121], v141 offset:6144
	s_add_u32 m0, s13, 0xf000
	v_lshl_add_u64 v[178:179], v[80:81], 0, s[14:15]
	global_load_lds_dwordx4 v[178:179], off
	v_mfma_f32_16x16x32_bf16 v[22:25], v[144:147], v[168:171], v[22:25]
	v_mfma_f32_16x16x32_bf16 v[18:21], v[148:151], v[168:171], v[18:21]
	v_mfma_f32_16x16x32_bf16 v[14:17], v[152:155], v[168:171], v[14:17]
	v_mfma_f32_16x16x32_bf16 v[10:13], v[156:159], v[168:171], v[10:13]
	v_mfma_f32_16x16x32_bf16 v[6:9], v[144:147], v[172:175], v[6:9]
	v_mfma_f32_16x16x32_bf16 v[2:5], v[148:151], v[172:175], v[2:5]
	v_mfma_f32_16x16x32_bf16 v[58:61], v[152:155], v[172:175], v[58:61]
	v_mfma_f32_16x16x32_bf16 v[62:65], v[156:159], v[172:175], v[62:65]
	s_add_u32 s14, s14, 0x80
	s_addc_u32 s15, s15, 0
	s_sub_u32 s16, s16, 1
	s_cmp_lg_u32 s16, 0
	s_cbranch_scc1 .Lgp_i43_loop
	s_waitcnt lgkmcnt(0)
	v_mfma_f32_16x16x32_bf16 v[54:57], v[90:93], v[106:109], v[54:57]
	ds_read_b128 v[144:147], v142 offset:17408
	v_mfma_f32_16x16x32_bf16 v[50:53], v[94:97], v[106:109], v[50:53]
	ds_read_b128 v[148:151], v142 offset:19456
	v_mfma_f32_16x16x32_bf16 v[46:49], v[98:101], v[106:109], v[46:49]
	ds_read_b128 v[152:155], v142 offset:21504
	v_mfma_f32_16x16x32_bf16 v[42:45], v[102:105], v[106:109], v[42:45]
	ds_read_b128 v[156:159], v142 offset:23552
	v_mfma_f32_16x16x32_bf16 v[38:41], v[90:93], v[110:113], v[38:41]
	ds_read_b128 v[160:163], v141 offset:1024
	v_mfma_f32_16x16x32_bf16 v[34:37], v[94:97], v[110:113], v[34:37]
	ds_read_b128 v[164:167], v141 offset:3072
	v_mfma_f32_16x16x32_bf16 v[30:33], v[98:101], v[110:113], v[30:33]
	ds_read_b128 v[168:171], v141 offset:5120
	v_mfma_f32_16x16x32_bf16 v[26:29], v[102:105], v[110:113], v[26:29]
	ds_read_b128 v[172:175], v141 offset:7168
	v_mfma_f32_16x16x32_bf16 v[22:25], v[90:93], v[114:117], v[22:25]
	v_mfma_f32_16x16x32_bf16 v[18:21], v[94:97], v[114:117], v[18:21]
	v_mfma_f32_16x16x32_bf16 v[14:17], v[98:101], v[114:117], v[14:17]
	v_mfma_f32_16x16x32_bf16 v[10:13], v[102:105], v[114:117], v[10:13]
	v_mfma_f32_16x16x32_bf16 v[6:9], v[90:93], v[118:121], v[6:9]
	v_mfma_f32_16x16x32_bf16 v[2:5], v[94:97], v[118:121], v[2:5]
	v_mfma_f32_16x16x32_bf16 v[58:61], v[98:101], v[118:121], v[58:61]
	v_mfma_f32_16x16x32_bf16 v[62:65], v[102:105], v[118:121], v[62:65]
	s_waitcnt vmcnt(0) lgkmcnt(0)
	s_barrier
	v_mfma_f32_16x16x32_bf16 v[54:57], v[144:147], v[160:163], v[54:57]
	v_mfma_f32_16x16x32_bf16 v[50:53], v[148:151], v[160:163], v[50:53]
	v_mfma_f32_16x16x32_bf16 v[46:49], v[152:155], v[160:163], v[46:49]
	v_mfma_f32_16x16x32_bf16 v[42:45], v[156:159], v[160:163], v[42:45]
	v_mfma_f32_16x16x32_bf16 v[38:41], v[144:147], v[164:167], v[38:41]
	v_mfma_f32_16x16x32_bf16 v[34:37], v[148:151], v[164:167], v[34:37]
	v_mfma_f32_16x16x32_bf16 v[30:33], v[152:155], v[164:167], v[30:33]
	v_mfma_f32_16x16x32_bf16 v[26:29], v[156:159], v[164:167], v[26:29]
	v_mfma_f32_16x16x32_bf16 v[22:25], v[144:147], v[168:171], v[22:25]
	v_mfma_f32_16x16x32_bf16 v[18:21], v[148:151], v[168:171], v[18:21]
	v_mfma_f32_16x16x32_bf16 v[14:17], v[152:155], v[168:171], v[14:17]
	v_mfma_f32_16x16x32_bf16 v[10:13], v[156:159], v[168:171], v[10:13]
	v_mfma_f32_16x16x32_bf16 v[6:9], v[144:147], v[172:175], v[6:9]
	v_mfma_f32_16x16x32_bf16 v[2:5], v[148:151], v[172:175], v[2:5]
	v_mfma_f32_16x16x32_bf16 v[58:61], v[152:155], v[172:175], v[58:61]
	v_mfma_f32_16x16x32_bf16 v[62:65], v[156:159], v[172:175], v[62:65]
	v_add3_u32 v0, 0, v83, v89
	ds_read_b128 v[66:69], v0 offset:49152
	ds_read_b128 v[70:73], v0 offset:51200
	ds_read_b128 v[74:77], v0 offset:53248
	ds_read_b128 v[78:81], v0 offset:55296
	v_add3_u32 v106, 0, v83, v87
	v_add3_u32 v110, 0, v84, v85
	ds_read_b128 v[90:93], v106 offset:32768
	ds_read_b128 v[94:97], v110 offset:32768
	v_add3_u32 v111, 0, v84, v88
	v_add3_u32 v112, 0, v84, v86
	ds_read_b128 v[98:101], v111 offset:32768
	ds_read_b128 v[82:85], v112 offset:32768
	s_waitcnt lgkmcnt(3)
	v_mfma_f32_16x16x32_bf16 v[54:57], v[66:69], v[90:93], v[54:57]
	s_add_i32 s21, s21, s83
	s_cmpk_gt_i32 s21, 0x1ff
	v_mfma_f32_16x16x32_bf16 v[50:53], v[70:73], v[90:93], v[50:53]
	ds_read_b128 v[86:89], v0 offset:50176
	v_mfma_f32_16x16x32_bf16 v[46:49], v[74:77], v[90:93], v[46:49]
	v_mfma_f32_16x16x32_bf16 v[42:45], v[78:81], v[90:93], v[42:45]
	ds_read_b128 v[90:93], v0 offset:52224
	s_waitcnt lgkmcnt(4)
	v_mfma_f32_16x16x32_bf16 v[38:41], v[66:69], v[94:97], v[38:41]
	v_mfma_f32_16x16x32_bf16 v[34:37], v[70:73], v[94:97], v[34:37]
	ds_read_b128 v[102:105], v0 offset:54272
	v_mfma_f32_16x16x32_bf16 v[30:33], v[74:77], v[94:97], v[30:33]
	v_mfma_f32_16x16x32_bf16 v[26:29], v[78:81], v[94:97], v[26:29]
	ds_read_b128 v[94:97], v0 offset:56320
	v_mov_b32_e32 v0, v133
	s_waitcnt lgkmcnt(5)
	v_mfma_f32_16x16x32_bf16 v[22:25], v[66:69], v[98:101], v[22:25]
	v_mfma_f32_16x16x32_bf16 v[18:21], v[70:73], v[98:101], v[18:21]
	ds_read_b128 v[106:109], v106 offset:33792
	v_mfma_f32_16x16x32_bf16 v[14:17], v[74:77], v[98:101], v[14:17]
	v_mfma_f32_16x16x32_bf16 v[10:13], v[78:81], v[98:101], v[10:13]
	ds_read_b128 v[98:101], v110 offset:33792
	s_waitcnt lgkmcnt(6)
	v_mfma_f32_16x16x32_bf16 v[6:9], v[66:69], v[82:85], v[6:9]
	v_mfma_f32_16x16x32_bf16 v[2:5], v[70:73], v[82:85], v[2:5]
	ds_read_b128 v[66:69], v111 offset:33792
	v_mfma_f32_16x16x32_bf16 v[58:61], v[74:77], v[82:85], v[58:61]
	v_mfma_f32_16x16x32_bf16 v[62:65], v[78:81], v[82:85], v[62:65]
	ds_read_b128 v[70:73], v112 offset:33792
	s_waitcnt vmcnt(0)
	s_waitcnt lgkmcnt(0)
	v_mfma_f32_16x16x32_bf16 v[74:77], v[90:93], v[66:69], v[18:21]
	s_barrier
	v_mfma_f32_16x16x32_bf16 v[18:21], v[94:97], v[66:69], v[10:13]
	v_mfma_f32_16x16x32_bf16 v[10:13], v[90:93], v[70:73], v[2:5]
	v_mfma_f32_16x16x32_bf16 v[2:5], v[102:105], v[70:73], v[58:61]
	s_nop 2
	v_ashrrev_i32_e32 v58, 1, v0
	v_mfma_f32_16x16x32_bf16 v[54:57], v[86:89], v[106:109], v[54:57]
	v_and_b32_e32 v58, 0xffffffc0, v58
	v_add_u32_e32 v58, s12, v58
	v_and_or_b32 v58, v0, 15, v58
	v_and_b32_e32 v59, 64, v0
	v_lshrrev_b32_e32 v0, 2, v0
	v_mfma_f32_16x16x32_bf16 v[50:53], v[90:93], v[106:109], v[50:53]
	v_and_b32_e32 v0, 12, v0
	v_or3_b32 v60, v59, v0, s10
	v_max_f32_e32 v0, v54, v54
	v_max_f32_e32 v54, v55, v55
	v_ashrrev_i32_e32 v59, 31, v58
	v_max_f32_e32 v0, 0, v0
	v_max_f32_e32 v54, 0, v54
	v_max_f32_e32 v55, v56, v56
	v_mfma_f32_16x16x32_bf16 v[46:49], v[102:105], v[106:109], v[46:49]
	v_max_f32_e32 v55, 0, v55
	v_mul_f32_e32 v0, v0, v0
	v_ashrrev_i32_e32 v61, 31, v60
	v_mfma_f32_16x16x32_bf16 v[78:81], v[102:105], v[66:69], v[14:17]
	v_max_f32_e32 v56, v57, v57
	v_max_f32_e32 v56, 0, v56
	v_mfma_f32_16x16x32_bf16 v[14:17], v[86:89], v[70:73], v[6:9]
	v_mfma_f32_16x16x32_bf16 v[6:9], v[94:97], v[70:73], v[62:65]
	s_nop 2
	v_lshlrev_b64 v[62:63], 13, v[58:59]
	v_mul_f32_e32 v59, v54, v54
	v_mul_f32_e32 v64, v55, v55
	v_lshlrev_b64 v[54:55], 1, v[60:61]
	v_cvt_pk_bf16_f32 v60, v0, v59
	v_max_f32_e32 v0, v50, v50
	v_max_f32_e32 v50, v51, v51
	v_max_f32_e32 v0, 0, v0
	v_max_f32_e32 v50, 0, v50
	v_mfma_f32_16x16x32_bf16 v[42:45], v[94:97], v[106:109], v[42:45]
	v_mul_f32_e32 v0, v0, v0
	v_mul_f32_e32 v50, v50, v50
	v_cvt_pk_bf16_f32 v50, v0, v50
	v_max_f32_e32 v0, v46, v46
	v_max_f32_e32 v46, v47, v47
	v_max_f32_e32 v0, 0, v0
	v_max_f32_e32 v46, 0, v46
	v_mfma_f32_16x16x32_bf16 v[38:41], v[86:89], v[98:101], v[38:41]
	v_mul_f32_e32 v0, v0, v0
	v_mul_f32_e32 v46, v46, v46
	v_cvt_pk_bf16_f32 v46, v0, v46
	v_max_f32_e32 v0, v42, v42
	v_max_f32_e32 v42, v43, v43
	v_max_f32_e32 v0, 0, v0
	v_max_f32_e32 v42, 0, v42
	v_mfma_f32_16x16x32_bf16 v[34:37], v[90:93], v[98:101], v[34:37]
	v_max_f32_e32 v43, v44, v44
	v_max_f32_e32 v44, v45, v45
	v_mul_f32_e32 v0, v0, v0
	v_mul_f32_e32 v42, v42, v42
	v_max_f32_e32 v43, 0, v43
	v_max_f32_e32 v44, 0, v44
	v_cvt_pk_bf16_f32 v42, v0, v42
	v_max_f32_e32 v0, v38, v38
	v_max_f32_e32 v38, v39, v39
	v_max_f32_e32 v39, v40, v40
	v_max_f32_e32 v40, v41, v41
	v_mul_f32_e32 v43, v43, v43
	v_mul_f32_e32 v44, v44, v44
	v_max_f32_e32 v0, 0, v0
	v_max_f32_e32 v38, 0, v38
	v_max_f32_e32 v39, 0, v39
	v_max_f32_e32 v40, 0, v40
	v_mfma_f32_16x16x32_bf16 v[30:33], v[102:105], v[98:101], v[30:33]
	v_cvt_pk_bf16_f32 v43, v43, v44
	v_mul_f32_e32 v0, v0, v0
	v_mul_f32_e32 v44, v38, v38
	v_mul_f32_e32 v41, v39, v39
	v_mul_f32_e32 v40, v40, v40
	v_cvt_pk_bf16_f32 v41, v41, v40
	v_cvt_pk_bf16_f32 v40, v0, v44
	v_max_f32_e32 v0, v34, v34
	v_max_f32_e32 v34, v35, v35
	v_max_f32_e32 v0, 0, v0
	v_max_f32_e32 v34, 0, v34
	v_mfma_f32_16x16x32_bf16 v[26:29], v[94:97], v[98:101], v[26:29]
	v_mul_f32_e32 v0, v0, v0
	v_mul_f32_e32 v34, v34, v34
	v_lshl_add_u64 v[62:63], s[4:5], 0, v[62:63]
	v_cvt_pk_bf16_f32 v34, v0, v34
	v_max_f32_e32 v0, v30, v30
	v_max_f32_e32 v30, v31, v31
	v_mul_f32_e32 v65, v56, v56
	v_lshl_add_u64 v[56:57], v[62:63], 0, v[54:55]
	v_max_f32_e32 v0, 0, v0
	v_max_f32_e32 v30, 0, v30
	global_store_dwordx2 v[56:57], v[42:43], off offset:96
	v_or_b32_e32 v42, 16, v58
	v_mul_f32_e32 v0, v0, v0
	v_mul_f32_e32 v30, v30, v30
	v_ashrrev_i32_e32 v43, 31, v42
	v_cvt_pk_bf16_f32 v30, v0, v30
	v_max_f32_e32 v0, v26, v26
	v_max_f32_e32 v26, v27, v27
	v_max_f32_e32 v27, v28, v28
	v_max_f32_e32 v28, v29, v29
	v_mfma_f32_16x16x32_bf16 v[22:25], v[86:89], v[66:69], v[22:25]
	v_lshlrev_b64 v[42:43], 13, v[42:43]
	v_max_f32_e32 v0, 0, v0
	v_max_f32_e32 v26, 0, v26
	v_max_f32_e32 v27, 0, v27
	v_max_f32_e32 v28, 0, v28
	v_lshl_add_u64 v[42:43], s[4:5], 0, v[42:43]
	v_mul_f32_e32 v0, v0, v0
	v_mul_f32_e32 v26, v26, v26
	v_mul_f32_e32 v27, v27, v27
	v_mul_f32_e32 v28, v28, v28
	v_lshl_add_u64 v[38:39], v[42:43], 0, v[54:55]
	v_cvt_pk_bf16_f32 v27, v27, v28
	v_cvt_pk_bf16_f32 v26, v0, v26
	global_store_dwordx2 v[38:39], v[26:27], off offset:96
	v_or_b32_e32 v26, 32, v58
	v_ashrrev_i32_e32 v27, 31, v26
	v_max_f32_e32 v0, v22, v22
	v_max_f32_e32 v22, v23, v23
	v_max_f32_e32 v23, v24, v24
	v_max_f32_e32 v24, v25, v25
	v_lshlrev_b64 v[26:27], 13, v[26:27]
	v_max_f32_e32 v0, 0, v0
	v_max_f32_e32 v22, 0, v22
	v_max_f32_e32 v23, 0, v23
	v_max_f32_e32 v24, 0, v24
	v_lshl_add_u64 v[26:27], s[4:5], 0, v[26:27]
	v_mul_f32_e32 v0, v0, v0
	v_mul_f32_e32 v28, v22, v22
	v_mul_f32_e32 v25, v23, v23
	v_mul_f32_e32 v24, v24, v24
	v_lshl_add_u64 v[22:23], v[26:27], 0, v[54:55]
	v_cvt_pk_bf16_f32 v25, v25, v24
	v_cvt_pk_bf16_f32 v24, v0, v28
	global_store_dwordx2 v[22:23], v[24:25], off
	v_max_f32_e32 v0, v74, v74
	v_max_f32_e32 v24, v75, v75
	v_max_f32_e32 v25, v76, v76
	v_max_f32_e32 v26, v77, v77
	v_max_f32_e32 v0, 0, v0
	v_max_f32_e32 v24, 0, v24
	v_max_f32_e32 v25, 0, v25
	v_max_f32_e32 v26, 0, v26
	v_mul_f32_e32 v0, v0, v0
	v_mul_f32_e32 v24, v24, v24
	v_mul_f32_e32 v25, v25, v25
	v_mul_f32_e32 v26, v26, v26
	v_cvt_pk_bf16_f32 v25, v25, v26
	v_cvt_pk_bf16_f32 v24, v0, v24
	global_store_dwordx2 v[22:23], v[24:25], off offset:32
	v_max_f32_e32 v0, v78, v78
	v_max_f32_e32 v24, v79, v79
	v_max_f32_e32 v0, 0, v0
	v_max_f32_e32 v24, 0, v24
	v_mul_f32_e32 v0, v0, v0
	v_mul_f32_e32 v24, v24, v24
	v_cvt_pk_bf16_f32 v24, v0, v24
	v_max_f32_e32 v0, v18, v18
	v_max_f32_e32 v18, v19, v19
	v_max_f32_e32 v0, 0, v0
	v_max_f32_e32 v18, 0, v18
	v_max_f32_e32 v19, v20, v20
	v_max_f32_e32 v20, v21, v21
	v_mul_f32_e32 v0, v0, v0
	v_mul_f32_e32 v18, v18, v18
	v_max_f32_e32 v19, 0, v19
	v_max_f32_e32 v20, 0, v20
	v_cvt_pk_bf16_f32 v18, v0, v18
	v_max_f32_e32 v0, v14, v14
	v_max_f32_e32 v14, v15, v15
	v_max_f32_e32 v15, v16, v16
	v_max_f32_e32 v16, v17, v17
	v_mul_f32_e32 v19, v19, v19
	v_mul_f32_e32 v20, v20, v20
	v_max_f32_e32 v0, 0, v0
	v_max_f32_e32 v14, 0, v14
	v_max_f32_e32 v15, 0, v15
	v_max_f32_e32 v16, 0, v16
	v_cvt_pk_bf16_f32 v19, v19, v20
	v_mul_f32_e32 v0, v0, v0
	v_mul_f32_e32 v20, v14, v14
	v_mul_f32_e32 v17, v15, v15
	v_mul_f32_e32 v16, v16, v16
	v_cvt_pk_bf16_f32 v17, v17, v16
	v_cvt_pk_bf16_f32 v16, v0, v20
	v_max_f32_e32 v0, v10, v10
	v_max_f32_e32 v10, v11, v11
	v_max_f32_e32 v0, 0, v0
	v_max_f32_e32 v10, 0, v10
	global_store_dwordx2 v[22:23], v[18:19], off offset:96
	v_or_b32_e32 v18, 48, v58
	v_mul_f32_e32 v0, v0, v0
	v_mul_f32_e32 v10, v10, v10
	v_ashrrev_i32_e32 v19, 31, v18
	v_cvt_pk_bf16_f32 v10, v0, v10
	v_max_f32_e32 v0, v2, v2
	v_max_f32_e32 v2, v3, v3
	v_max_f32_e32 v3, v4, v4
	v_max_f32_e32 v4, v5, v5
	v_lshlrev_b64 v[18:19], 13, v[18:19]
	v_max_f32_e32 v0, 0, v0
	v_max_f32_e32 v2, 0, v2
	v_max_f32_e32 v3, 0, v3
	v_max_f32_e32 v4, 0, v4
	v_lshl_add_u64 v[18:19], s[4:5], 0, v[18:19]
	v_mul_f32_e32 v0, v0, v0
	v_mul_f32_e32 v2, v2, v2
	v_mul_f32_e32 v3, v3, v3
	v_mul_f32_e32 v4, v4, v4
	v_lshl_add_u64 v[14:15], v[18:19], 0, v[54:55]
	v_cvt_pk_bf16_f32 v3, v3, v4
	v_cvt_pk_bf16_f32 v2, v0, v2
	v_max_f32_e32 v51, v52, v52
	v_max_f32_e32 v52, v53, v53
	v_max_f32_e32 v47, v48, v48
	v_max_f32_e32 v48, v49, v49
	v_max_f32_e32 v35, v36, v36
	v_max_f32_e32 v36, v37, v37
	v_max_f32_e32 v31, v32, v32
	v_max_f32_e32 v32, v33, v33
	v_max_f32_e32 v25, v80, v80
	v_max_f32_e32 v26, v81, v81
	v_max_f32_e32 v11, v12, v12
	v_max_f32_e32 v12, v13, v13
	global_store_dwordx2 v[14:15], v[2:3], off offset:64
	v_max_f32_e32 v0, v6, v6
	v_max_f32_e32 v2, v7, v7
	v_max_f32_e32 v3, v8, v8
	v_max_f32_e32 v4, v9, v9
	v_max_f32_e32 v51, 0, v51
	v_max_f32_e32 v52, 0, v52
	v_max_f32_e32 v47, 0, v47
	v_max_f32_e32 v48, 0, v48
	v_max_f32_e32 v35, 0, v35
	v_max_f32_e32 v36, 0, v36
	v_max_f32_e32 v31, 0, v31
	v_max_f32_e32 v32, 0, v32
	v_max_f32_e32 v25, 0, v25
	v_max_f32_e32 v26, 0, v26
	v_max_f32_e32 v11, 0, v11
	v_max_f32_e32 v12, 0, v12
	v_max_f32_e32 v0, 0, v0
	v_max_f32_e32 v2, 0, v2
	v_max_f32_e32 v3, 0, v3
	v_max_f32_e32 v4, 0, v4
	v_mul_f32_e32 v51, v51, v51
	v_mul_f32_e32 v52, v52, v52
	v_mul_f32_e32 v47, v47, v47
	v_mul_f32_e32 v48, v48, v48
	v_mul_f32_e32 v35, v35, v35
	v_mul_f32_e32 v36, v36, v36
	v_mul_f32_e32 v31, v31, v31
	v_mul_f32_e32 v32, v32, v32
	v_mul_f32_e32 v25, v25, v25
	v_mul_f32_e32 v26, v26, v26
	v_mul_f32_e32 v11, v11, v11
	v_mul_f32_e32 v12, v12, v12
	v_mul_f32_e32 v0, v0, v0
	v_mul_f32_e32 v2, v2, v2
	v_mul_f32_e32 v3, v3, v3
	v_mul_f32_e32 v4, v4, v4
	v_cvt_pk_bf16_f32 v61, v64, v65
	v_cvt_pk_bf16_f32 v51, v51, v52
	v_cvt_pk_bf16_f32 v47, v47, v48
	v_cvt_pk_bf16_f32 v35, v35, v36
	v_cvt_pk_bf16_f32 v31, v31, v32
	v_cvt_pk_bf16_f32 v25, v25, v26
	v_cvt_pk_bf16_f32 v11, v11, v12
	v_cvt_pk_bf16_f32 v3, v3, v4
	v_cvt_pk_bf16_f32 v2, v0, v2
	global_store_dwordx2 v[56:57], v[60:61], off
	global_store_dwordx2 v[56:57], v[50:51], off offset:32
	global_store_dwordx2 v[56:57], v[46:47], off offset:64
	global_store_dwordx2 v[38:39], v[40:41], off
	global_store_dwordx2 v[38:39], v[34:35], off offset:32
	global_store_dwordx2 v[38:39], v[30:31], off offset:64
	global_store_dwordx2 v[22:23], v[24:25], off offset:64
	global_store_dwordx2 v[14:15], v[16:17], off
	global_store_dwordx2 v[14:15], v[10:11], off offset:32
	global_store_dwordx2 v[14:15], v[2:3], off offset:96
	s_cbranch_scc0 .LBB0_42

.LBB0_63:
	s_ashr_i32 s6, s21, 31
	s_lshr_b32 s6, s6, 26
	s_add_i32 s6, s21, s6
	s_andn2_b32 s6, s6, 63
	s_sub_i32 s7, s21, s6
	s_bfe_i32 s12, s7, 0x80000
	s_bfe_u32 s12, s12, 0x3000c
	s_add_i32 s12, s7, s12
	s_bfe_i32 s13, s12, 0x80000
	s_sext_i32_i16 s13, s13
	s_and_b32 s12, s12, 0xf8
	s_sub_i32 s7, s7, s12
	s_ashr_i32 s12, s13, 3
	s_or_b32 s22, s96, s6
	s_add_i32 s22, s22, s12
	s_waitcnt vmcnt(9)
	v_mov_b32_e32 v26, v133
	s_lshl_b32 s12, s22, 7
	s_sext_i32_i8 s7, s7
	v_lshlrev_b32_e32 v16, 4, v26
	v_and_b32_e32 v0, 32, v26
	s_ashr_i32 s13, s12, 31
	v_bitop3_b32 v0, v16, v0, 48 bitop3:0x6c
	s_lshl_b32 s6, s7, 7
	s_lshl_b64 s[14:15], s[12:13], 11
	v_lshrrev_b32_e32 v17, 2, v26
	v_lshrrev_b32_e32 v2, 1, v26
	v_lshrrev_b32_e32 v0, 1, v0
	v_ashrrev_i32_e32 v4, 3, v26
	s_add_u32 s24, s3, s14
	v_and_b32_e32 v27, 0xfffffc00, v16
	v_and_or_b32 v0, v2, 32, v0
	v_bfi_b32 v4, -16, v4, v17
	s_addc_u32 s25, s18, s15
	s_ashr_i32 s7, s6, 31
	v_lshlrev_b32_e32 v0, 1, v0
	v_ashrrev_i32_e32 v5, 31, v4
	v_add_u32_e32 v8, 0x1000, v16
	v_add_u32_e32 v82, 0, v27
	s_lshl_b64 s[16:17], s[6:7], 11
	v_lshl_add_u64 v[2:3], s[24:25], 0, v[0:1]
	v_lshlrev_b64 v[4:5], 11, v[4:5]
	v_ashrrev_i32_e32 v8, 7, v8
	v_add_u32_e32 v12, 0x2000, v16
	v_readfirstlane_b32 s7, v82
	v_lshl_add_u64 v[6:7], v[2:3], 0, v[4:5]
	v_bfi_b32 v8, -16, v8, v17
	v_ashrrev_i32_e32 v12, 7, v12
	v_add_u32_e32 v16, 0x3000, v16
	s_mov_b32 m0, s7
	v_ashrrev_i32_e32 v9, 31, v8
	v_bfi_b32 v12, -16, v12, v17
	v_ashrrev_i32_e32 v16, 7, v16
	s_barrier
	global_load_lds_dwordx4 v[6:7], off
	v_add_u32_e32 v6, 0x1000, v82
	v_lshlrev_b64 v[8:9], 11, v[8:9]
	v_ashrrev_i32_e32 v13, 31, v12
	v_bfi_b32 v16, -16, v16, v17
	v_readfirstlane_b32 s7, v6
	v_add_u32_e32 v6, 0x2000, v82
	v_lshl_add_u64 v[10:11], v[2:3], 0, v[8:9]
	v_lshlrev_b64 v[12:13], 11, v[12:13]
	v_ashrrev_i32_e32 v17, 31, v16
	s_mov_b32 m0, s7
	v_readfirstlane_b32 s7, v6
	v_add_u32_e32 v6, 0x3000, v82
	v_lshl_add_u64 v[14:15], v[2:3], 0, v[12:13]
	v_lshlrev_b64 v[16:17], 11, v[16:17]
	global_load_lds_dwordx4 v[10:11], off
	s_mov_b32 m0, s7
	v_readfirstlane_b32 s7, v6
	s_add_u32 s26, s19, s16
	v_lshl_add_u64 v[2:3], v[2:3], 0, v[16:17]
	global_load_lds_dwordx4 v[14:15], off
	s_mov_b32 m0, s7
	s_addc_u32 s27, s20, s17
	global_load_lds_dwordx4 v[2:3], off
	v_add_u32_e32 v2, 0x4000, v82
	v_lshl_add_u64 v[18:19], s[26:27], 0, v[0:1]
	v_readfirstlane_b32 s7, v2
	v_add_u32_e32 v2, 0x5000, v82
	v_lshl_add_u64 v[20:21], v[18:19], 0, v[4:5]
	s_mov_b32 m0, s7
	v_readfirstlane_b32 s7, v2
	v_add_u32_e32 v2, 0x6000, v82
	v_lshl_add_u64 v[22:23], v[18:19], 0, v[8:9]
	global_load_lds_dwordx4 v[20:21], off
	s_mov_b32 m0, s7
	v_readfirstlane_b32 s7, v2
	v_add_u32_e32 v2, 0x7000, v82
	v_lshl_add_u64 v[24:25], v[18:19], 0, v[12:13]
	global_load_lds_dwordx4 v[22:23], off
	s_mov_b32 m0, s7
	v_readfirstlane_b32 s7, v2
	v_lshl_add_u64 v[18:19], v[18:19], 0, v[16:17]
	global_load_lds_dwordx4 v[24:25], off
	s_mov_b32 m0, s7
	v_and_b32_e32 v2, 15, v26
	global_load_lds_dwordx4 v[18:19], off
	v_lshlrev_b32_e32 v6, 2, v26
	v_and_b32_e32 v3, 48, v26
	v_lshlrev_b32_e32 v2, 6, v2
	v_and_b32_e32 v6, 32, v6
	v_bitop3_b32 v83, v2, v6, v3 bitop3:0x36
	v_lshlrev_b32_e32 v2, 7, v26
	v_and_b32_e32 v89, 0x2000, v2
	v_lshlrev_b32_e32 v2, 6, v26
	v_and_b32_e32 v87, 0xffffe000, v2
	v_and_b32_e32 v2, 0x3c0, v2
	v_bitop3_b32 v84, v2, v6, v3 bitop3:0x36
	v_lshl_add_u64 v[2:3], s[16:17], 0, v[16:17]
	v_or_b32_e32 v2, v2, v0
	v_lshl_add_u64 v[66:67], s[8:9], 0, v[2:3]
	v_lshl_add_u64 v[2:3], s[16:17], 0, v[12:13]
	v_or_b32_e32 v2, v2, v0
	v_lshl_add_u64 v[68:69], s[8:9], 0, v[2:3]
	v_lshl_add_u64 v[2:3], s[16:17], 0, v[8:9]
	v_or_b32_e32 v2, v2, v0
	v_lshl_add_u64 v[70:71], s[8:9], 0, v[2:3]
	v_lshl_add_u64 v[2:3], s[16:17], 0, v[4:5]
	v_or_b32_e32 v2, v2, v0
	v_lshl_add_u64 v[72:73], s[8:9], 0, v[2:3]
	v_lshl_add_u64 v[2:3], s[14:15], 0, v[16:17]
	v_or_b32_e32 v2, v2, v0
	v_lshl_add_u64 v[74:75], s[10:11], 0, v[2:3]
	v_lshl_add_u64 v[2:3], s[14:15], 0, v[12:13]
	v_or_b32_e32 v2, v2, v0
	v_lshl_add_u64 v[76:77], s[10:11], 0, v[2:3]
	v_lshl_add_u64 v[2:3], s[14:15], 0, v[8:9]
	v_or_b32_e32 v2, v2, v0
	s_waitcnt vmcnt(0)
	v_lshl_add_u64 v[78:79], s[10:11], 0, v[2:3]
	v_lshl_add_u64 v[2:3], s[14:15], 0, v[4:5]
	v_or_b32_e32 v2, v2, v0
	v_mov_b32_e32 v58, 0
	v_or_b32_e32 v85, 0x800, v87
	v_or_b32_e32 v88, 0x1000, v87
	v_or_b32_e32 v86, 0x1800, v87
	v_lshl_add_u64 v[80:81], s[10:11], 0, v[2:3]
	s_mov_b64 s[14:15], 0
	s_mov_b32 s7, 0
	v_mov_b32_e32 v59, v58
	v_mov_b32_e32 v60, v58
	v_mov_b32_e32 v61, v58
	s_waitcnt vmcnt(0)
	v_mov_b32_e32 v46, v58
	v_mov_b32_e32 v47, v58
	v_mov_b32_e32 v48, v58
	v_mov_b32_e32 v49, v58
	v_mov_b32_e32 v2, v58
	v_mov_b32_e32 v3, v58
	v_mov_b32_e32 v4, v58
	v_mov_b32_e32 v5, v58
	v_mov_b32_e32 v6, v58
	v_mov_b32_e32 v7, v58
	v_mov_b32_e32 v8, v58
	v_mov_b32_e32 v9, v58
	v_mov_b32_e32 v10, v58
	v_mov_b32_e32 v11, v58
	v_mov_b32_e32 v12, v58
	v_mov_b32_e32 v13, v58
	v_mov_b32_e32 v14, v58
	v_mov_b32_e32 v15, v58
	v_mov_b32_e32 v16, v58
	v_mov_b32_e32 v17, v58
	v_mov_b32_e32 v18, v58
	v_mov_b32_e32 v19, v58
	v_mov_b32_e32 v20, v58
	v_mov_b32_e32 v21, v58
	v_mov_b32_e32 v22, v58
	v_mov_b32_e32 v23, v58
	v_mov_b32_e32 v24, v58
	v_mov_b32_e32 v25, v58
	v_mov_b32_e32 v26, v58
	v_mov_b32_e32 v27, v58
	v_mov_b32_e32 v28, v58
	v_mov_b32_e32 v29, v58
	v_mov_b32_e32 v30, v58
	v_mov_b32_e32 v31, v58
	v_mov_b32_e32 v32, v58
	v_mov_b32_e32 v33, v58
	v_mov_b32_e32 v34, v58
	v_mov_b32_e32 v35, v58
	v_mov_b32_e32 v36, v58
	v_mov_b32_e32 v37, v58
	v_mov_b32_e32 v38, v58
	v_mov_b32_e32 v39, v58
	v_mov_b32_e32 v40, v58
	v_mov_b32_e32 v41, v58
	v_mov_b32_e32 v42, v58
	v_mov_b32_e32 v43, v58
	v_mov_b32_e32 v44, v58
	v_mov_b32_e32 v45, v58
	v_mov_b32_e32 v50, v58
	v_mov_b32_e32 v51, v58
	v_mov_b32_e32 v52, v58
	v_mov_b32_e32 v53, v58
	v_mov_b32_e32 v54, v58
	v_mov_b32_e32 v55, v58
	v_mov_b32_e32 v56, v58
	v_mov_b32_e32 v57, v58
	v_mov_b32_e32 v62, v58
	v_mov_b32_e32 v63, v58
	v_mov_b32_e32 v64, v58
	v_mov_b32_e32 v65, v58
	s_waitcnt vmcnt(0) lgkmcnt(0)
	s_barrier
	v_readfirstlane_b32 s13, v82
	v_add_u32_e32 v141, v83, v87
	v_add_u32_e32 v142, v83, v89
	ds_read_b128 v[90:93], v142 offset:16384
	ds_read_b128 v[94:97], v142 offset:18432
	ds_read_b128 v[98:101], v142 offset:20480
	ds_read_b128 v[102:105], v142 offset:22528
	ds_read_b128 v[106:109], v141
	ds_read_b128 v[110:113], v141 offset:2048
	ds_read_b128 v[114:117], v141 offset:4096
	ds_read_b128 v[118:121], v141 offset:6144
	s_add_u32 m0, s13, 0x8000
	v_lshl_add_u64 v[176:177], v[80:81], 0, s[14:15]
	global_load_lds_dwordx4 v[176:177], off
	s_add_u32 m0, s13, 0x9000
	v_lshl_add_u64 v[178:179], v[78:79], 0, s[14:15]
	global_load_lds_dwordx4 v[178:179], off
	s_add_u32 m0, s13, 0xa000
	v_lshl_add_u64 v[176:177], v[76:77], 0, s[14:15]
	global_load_lds_dwordx4 v[176:177], off
	s_add_u32 m0, s13, 0xb000
	v_lshl_add_u64 v[178:179], v[74:75], 0, s[14:15]
	global_load_lds_dwordx4 v[178:179], off
	s_add_u32 m0, s13, 0xc000
	v_lshl_add_u64 v[176:177], v[72:73], 0, s[14:15]
	global_load_lds_dwordx4 v[176:177], off
	s_add_u32 m0, s13, 0xd000
	v_lshl_add_u64 v[178:179], v[70:71], 0, s[14:15]
	global_load_lds_dwordx4 v[178:179], off
	s_add_u32 m0, s13, 0xe000
	v_lshl_add_u64 v[176:177], v[68:69], 0, s[14:15]
	global_load_lds_dwordx4 v[176:177], off
	s_add_u32 m0, s13, 0xf000
	v_lshl_add_u64 v[178:179], v[66:67], 0, s[14:15]
	global_load_lds_dwordx4 v[178:179], off
	s_add_u32 s14, s14, 0x80
	s_addc_u32 s15, s15, 0
	s_mov_b32 s16, 7
.Lgp_i64_loop:
	s_waitcnt lgkmcnt(0)
	v_mfma_f32_16x16x32_bf16 v[62:65], v[90:93], v[106:109], v[62:65]
	ds_read_b128 v[144:147], v142 offset:17408
	v_mfma_f32_16x16x32_bf16 v[54:57], v[94:97], v[106:109], v[54:57]
	ds_read_b128 v[148:151], v142 offset:19456
	v_mfma_f32_16x16x32_bf16 v[50:53], v[98:101], v[106:109], v[50:53]
	ds_read_b128 v[152:155], v142 offset:21504
	v_mfma_f32_16x16x32_bf16 v[42:45], v[102:105], v[106:109], v[42:45]
	ds_read_b128 v[156:159], v142 offset:23552
	v_mfma_f32_16x16x32_bf16 v[38:41], v[90:93], v[110:113], v[38:41]
	ds_read_b128 v[160:163], v141 offset:1024
	v_mfma_f32_16x16x32_bf16 v[34:37], v[94:97], v[110:113], v[34:37]
	ds_read_b128 v[164:167], v141 offset:3072
	v_mfma_f32_16x16x32_bf16 v[30:33], v[98:101], v[110:113], v[30:33]
	ds_read_b128 v[168:171], v141 offset:5120
	v_mfma_f32_16x16x32_bf16 v[26:29], v[102:105], v[110:113], v[26:29]
	ds_read_b128 v[172:175], v141 offset:7168
	v_mfma_f32_16x16x32_bf16 v[22:25], v[90:93], v[114:117], v[22:25]
	v_mfma_f32_16x16x32_bf16 v[18:21], v[94:97], v[114:117], v[18:21]
	v_mfma_f32_16x16x32_bf16 v[14:17], v[98:101], v[114:117], v[14:17]
	v_mfma_f32_16x16x32_bf16 v[10:13], v[102:105], v[114:117], v[10:13]
	v_mfma_f32_16x16x32_bf16 v[6:9], v[90:93], v[118:121], v[6:9]
	v_mfma_f32_16x16x32_bf16 v[2:5], v[94:97], v[118:121], v[2:5]
	v_mfma_f32_16x16x32_bf16 v[46:49], v[98:101], v[118:121], v[46:49]
	v_mfma_f32_16x16x32_bf16 v[58:61], v[102:105], v[118:121], v[58:61]
	s_waitcnt vmcnt(0) lgkmcnt(0)
	s_barrier
	v_mfma_f32_16x16x32_bf16 v[62:65], v[144:147], v[160:163], v[62:65]
	ds_read_b128 v[90:93], v142 offset:49152
	s_add_u32 m0, s13, 0x0
	v_lshl_add_u64 v[176:177], v[80:81], 0, s[14:15]
	global_load_lds_dwordx4 v[176:177], off
	v_mfma_f32_16x16x32_bf16 v[54:57], v[148:151], v[160:163], v[54:57]
	ds_read_b128 v[94:97], v142 offset:51200
	s_add_u32 m0, s13, 0x1000
	v_lshl_add_u64 v[178:179], v[78:79], 0, s[14:15]
	global_load_lds_dwordx4 v[178:179], off
	v_mfma_f32_16x16x32_bf16 v[50:53], v[152:155], v[160:163], v[50:53]
	ds_read_b128 v[98:101], v142 offset:53248
	s_add_u32 m0, s13, 0x2000
	v_lshl_add_u64 v[176:177], v[76:77], 0, s[14:15]
	global_load_lds_dwordx4 v[176:177], off
	v_mfma_f32_16x16x32_bf16 v[42:45], v[156:159], v[160:163], v[42:45]
	ds_read_b128 v[102:105], v142 offset:55296
	s_add_u32 m0, s13, 0x3000
	v_lshl_add_u64 v[178:179], v[74:75], 0, s[14:15]
	global_load_lds_dwordx4 v[178:179], off
	v_mfma_f32_16x16x32_bf16 v[38:41], v[144:147], v[164:167], v[38:41]
	ds_read_b128 v[106:109], v141 offset:32768
	s_add_u32 m0, s13, 0x4000
	v_lshl_add_u64 v[176:177], v[72:73], 0, s[14:15]
	global_load_lds_dwordx4 v[176:177], off
	v_mfma_f32_16x16x32_bf16 v[34:37], v[148:151], v[164:167], v[34:37]
	ds_read_b128 v[110:113], v141 offset:34816
	s_add_u32 m0, s13, 0x5000
	v_lshl_add_u64 v[178:179], v[70:71], 0, s[14:15]
	global_load_lds_dwordx4 v[178:179], off
	v_mfma_f32_16x16x32_bf16 v[30:33], v[152:155], v[164:167], v[30:33]
	ds_read_b128 v[114:117], v141 offset:36864
	s_add_u32 m0, s13, 0x6000
	v_lshl_add_u64 v[176:177], v[68:69], 0, s[14:15]
	global_load_lds_dwordx4 v[176:177], off
	v_mfma_f32_16x16x32_bf16 v[26:29], v[156:159], v[164:167], v[26:29]
	ds_read_b128 v[118:121], v141 offset:38912
	s_add_u32 m0, s13, 0x7000
	v_lshl_add_u64 v[178:179], v[66:67], 0, s[14:15]
	global_load_lds_dwordx4 v[178:179], off
	v_mfma_f32_16x16x32_bf16 v[22:25], v[144:147], v[168:171], v[22:25]
	v_mfma_f32_16x16x32_bf16 v[18:21], v[148:151], v[168:171], v[18:21]
	v_mfma_f32_16x16x32_bf16 v[14:17], v[152:155], v[168:171], v[14:17]
	v_mfma_f32_16x16x32_bf16 v[10:13], v[156:159], v[168:171], v[10:13]
	v_mfma_f32_16x16x32_bf16 v[6:9], v[144:147], v[172:175], v[6:9]
	v_mfma_f32_16x16x32_bf16 v[2:5], v[148:151], v[172:175], v[2:5]
	v_mfma_f32_16x16x32_bf16 v[46:49], v[152:155], v[172:175], v[46:49]
	v_mfma_f32_16x16x32_bf16 v[58:61], v[156:159], v[172:175], v[58:61]
	s_add_u32 s14, s14, 0x80
	s_addc_u32 s15, s15, 0
	s_waitcnt lgkmcnt(0)
	v_mfma_f32_16x16x32_bf16 v[62:65], v[90:93], v[106:109], v[62:65]
	ds_read_b128 v[144:147], v142 offset:50176
	v_mfma_f32_16x16x32_bf16 v[54:57], v[94:97], v[106:109], v[54:57]
	ds_read_b128 v[148:151], v142 offset:52224
	v_mfma_f32_16x16x32_bf16 v[50:53], v[98:101], v[106:109], v[50:53]
	ds_read_b128 v[152:155], v142 offset:54272
	v_mfma_f32_16x16x32_bf16 v[42:45], v[102:105], v[106:109], v[42:45]
	ds_read_b128 v[156:159], v142 offset:56320
	v_mfma_f32_16x16x32_bf16 v[38:41], v[90:93], v[110:113], v[38:41]
	ds_read_b128 v[160:163], v141 offset:33792
	v_mfma_f32_16x16x32_bf16 v[34:37], v[94:97], v[110:113], v[34:37]
	ds_read_b128 v[164:167], v141 offset:35840
	v_mfma_f32_16x16x32_bf16 v[30:33], v[98:101], v[110:113], v[30:33]
	ds_read_b128 v[168:171], v141 offset:37888
	v_mfma_f32_16x16x32_bf16 v[26:29], v[102:105], v[110:113], v[26:29]
	ds_read_b128 v[172:175], v141 offset:39936
	v_mfma_f32_16x16x32_bf16 v[22:25], v[90:93], v[114:117], v[22:25]
	v_mfma_f32_16x16x32_bf16 v[18:21], v[94:97], v[114:117], v[18:21]
	v_mfma_f32_16x16x32_bf16 v[14:17], v[98:101], v[114:117], v[14:17]
	v_mfma_f32_16x16x32_bf16 v[10:13], v[102:105], v[114:117], v[10:13]
	v_mfma_f32_16x16x32_bf16 v[6:9], v[90:93], v[118:121], v[6:9]
	v_mfma_f32_16x16x32_bf16 v[2:5], v[94:97], v[118:121], v[2:5]
	v_mfma_f32_16x16x32_bf16 v[46:49], v[98:101], v[118:121], v[46:49]
	v_mfma_f32_16x16x32_bf16 v[58:61], v[102:105], v[118:121], v[58:61]
	s_waitcnt vmcnt(0) lgkmcnt(0)
	s_barrier
	v_mfma_f32_16x16x32_bf16 v[62:65], v[144:147], v[160:163], v[62:65]
	ds_read_b128 v[90:93], v142 offset:16384
	s_add_u32 m0, s13, 0x8000
	v_lshl_add_u64 v[176:177], v[80:81], 0, s[14:15]
	global_load_lds_dwordx4 v[176:177], off
	v_mfma_f32_16x16x32_bf16 v[54:57], v[148:151], v[160:163], v[54:57]
	ds_read_b128 v[94:97], v142 offset:18432
	s_add_u32 m0, s13, 0x9000
	v_lshl_add_u64 v[178:179], v[78:79], 0, s[14:15]
	global_load_lds_dwordx4 v[178:179], off
	v_mfma_f32_16x16x32_bf16 v[50:53], v[152:155], v[160:163], v[50:53]
	ds_read_b128 v[98:101], v142 offset:20480
	s_add_u32 m0, s13, 0xa000
	v_lshl_add_u64 v[176:177], v[76:77], 0, s[14:15]
	global_load_lds_dwordx4 v[176:177], off
	v_mfma_f32_16x16x32_bf16 v[42:45], v[156:159], v[160:163], v[42:45]
	ds_read_b128 v[102:105], v142 offset:22528
	s_add_u32 m0, s13, 0xb000
	v_lshl_add_u64 v[178:179], v[74:75], 0, s[14:15]
	global_load_lds_dwordx4 v[178:179], off
	v_mfma_f32_16x16x32_bf16 v[38:41], v[144:147], v[164:167], v[38:41]
	ds_read_b128 v[106:109], v141
	s_add_u32 m0, s13, 0xc000
	v_lshl_add_u64 v[176:177], v[72:73], 0, s[14:15]
	global_load_lds_dwordx4 v[176:177], off
	v_mfma_f32_16x16x32_bf16 v[34:37], v[148:151], v[164:167], v[34:37]
	ds_read_b128 v[110:113], v141 offset:2048
	s_add_u32 m0, s13, 0xd000
	v_lshl_add_u64 v[178:179], v[70:71], 0, s[14:15]
	global_load_lds_dwordx4 v[178:179], off
	v_mfma_f32_16x16x32_bf16 v[30:33], v[152:155], v[164:167], v[30:33]
	ds_read_b128 v[114:117], v141 offset:4096
	s_add_u32 m0, s13, 0xe000
	v_lshl_add_u64 v[176:177], v[68:69], 0, s[14:15]
	global_load_lds_dwordx4 v[176:177], off
	v_mfma_f32_16x16x32_bf16 v[26:29], v[156:159], v[164:167], v[26:29]
	ds_read_b128 v[118:121], v141 offset:6144
	s_add_u32 m0, s13, 0xf000
	v_lshl_add_u64 v[178:179], v[66:67], 0, s[14:15]
	global_load_lds_dwordx4 v[178:179], off
	v_mfma_f32_16x16x32_bf16 v[22:25], v[144:147], v[168:171], v[22:25]
	v_mfma_f32_16x16x32_bf16 v[18:21], v[148:151], v[168:171], v[18:21]
	v_mfma_f32_16x16x32_bf16 v[14:17], v[152:155], v[168:171], v[14:17]
	v_mfma_f32_16x16x32_bf16 v[10:13], v[156:159], v[168:171], v[10:13]
	v_mfma_f32_16x16x32_bf16 v[6:9], v[144:147], v[172:175], v[6:9]
	v_mfma_f32_16x16x32_bf16 v[2:5], v[148:151], v[172:175], v[2:5]
	v_mfma_f32_16x16x32_bf16 v[46:49], v[152:155], v[172:175], v[46:49]
	v_mfma_f32_16x16x32_bf16 v[58:61], v[156:159], v[172:175], v[58:61]
	s_add_u32 s14, s14, 0x80
	s_addc_u32 s15, s15, 0
	s_sub_u32 s16, s16, 1
	s_cmp_lg_u32 s16, 0
	s_cbranch_scc1 .Lgp_i64_loop
	s_waitcnt lgkmcnt(0)
	v_mfma_f32_16x16x32_bf16 v[62:65], v[90:93], v[106:109], v[62:65]
	ds_read_b128 v[144:147], v142 offset:17408
	v_mfma_f32_16x16x32_bf16 v[54:57], v[94:97], v[106:109], v[54:57]
	ds_read_b128 v[148:151], v142 offset:19456
	v_mfma_f32_16x16x32_bf16 v[50:53], v[98:101], v[106:109], v[50:53]
	ds_read_b128 v[152:155], v142 offset:21504
	v_mfma_f32_16x16x32_bf16 v[42:45], v[102:105], v[106:109], v[42:45]
	ds_read_b128 v[156:159], v142 offset:23552
	v_mfma_f32_16x16x32_bf16 v[38:41], v[90:93], v[110:113], v[38:41]
	ds_read_b128 v[160:163], v141 offset:1024
	v_mfma_f32_16x16x32_bf16 v[34:37], v[94:97], v[110:113], v[34:37]
	ds_read_b128 v[164:167], v141 offset:3072
	v_mfma_f32_16x16x32_bf16 v[30:33], v[98:101], v[110:113], v[30:33]
	ds_read_b128 v[168:171], v141 offset:5120
	v_mfma_f32_16x16x32_bf16 v[26:29], v[102:105], v[110:113], v[26:29]
	ds_read_b128 v[172:175], v141 offset:7168
	v_mfma_f32_16x16x32_bf16 v[22:25], v[90:93], v[114:117], v[22:25]
	v_mfma_f32_16x16x32_bf16 v[18:21], v[94:97], v[114:117], v[18:21]
	v_mfma_f32_16x16x32_bf16 v[14:17], v[98:101], v[114:117], v[14:17]
	v_mfma_f32_16x16x32_bf16 v[10:13], v[102:105], v[114:117], v[10:13]
	v_mfma_f32_16x16x32_bf16 v[6:9], v[90:93], v[118:121], v[6:9]
	v_mfma_f32_16x16x32_bf16 v[2:5], v[94:97], v[118:121], v[2:5]
	v_mfma_f32_16x16x32_bf16 v[46:49], v[98:101], v[118:121], v[46:49]
	v_mfma_f32_16x16x32_bf16 v[58:61], v[102:105], v[118:121], v[58:61]
	s_waitcnt vmcnt(0) lgkmcnt(0)
	s_barrier
	v_mfma_f32_16x16x32_bf16 v[62:65], v[144:147], v[160:163], v[62:65]
	v_mfma_f32_16x16x32_bf16 v[54:57], v[148:151], v[160:163], v[54:57]
	v_mfma_f32_16x16x32_bf16 v[50:53], v[152:155], v[160:163], v[50:53]
	v_mfma_f32_16x16x32_bf16 v[42:45], v[156:159], v[160:163], v[42:45]
	v_mfma_f32_16x16x32_bf16 v[38:41], v[144:147], v[164:167], v[38:41]
	v_mfma_f32_16x16x32_bf16 v[34:37], v[148:151], v[164:167], v[34:37]
	v_mfma_f32_16x16x32_bf16 v[30:33], v[152:155], v[164:167], v[30:33]
	v_mfma_f32_16x16x32_bf16 v[26:29], v[156:159], v[164:167], v[26:29]
	v_mfma_f32_16x16x32_bf16 v[22:25], v[144:147], v[168:171], v[22:25]
	v_mfma_f32_16x16x32_bf16 v[18:21], v[148:151], v[168:171], v[18:21]
	v_mfma_f32_16x16x32_bf16 v[14:17], v[152:155], v[168:171], v[14:17]
	v_mfma_f32_16x16x32_bf16 v[10:13], v[156:159], v[168:171], v[10:13]
	v_mfma_f32_16x16x32_bf16 v[6:9], v[144:147], v[172:175], v[6:9]
	v_mfma_f32_16x16x32_bf16 v[2:5], v[148:151], v[172:175], v[2:5]
	v_mfma_f32_16x16x32_bf16 v[46:49], v[152:155], v[172:175], v[46:49]
	v_mfma_f32_16x16x32_bf16 v[58:61], v[156:159], v[172:175], v[58:61]
	v_add3_u32 v0, 0, v83, v89
	ds_read_b128 v[66:69], v0 offset:49152
	ds_read_b128 v[70:73], v0 offset:51200
	ds_read_b128 v[74:77], v0 offset:53248
	ds_read_b128 v[78:81], v0 offset:55296
	v_add3_u32 v114, 0, v83, v87
	v_add3_u32 v118, 0, v84, v85
	ds_read_b128 v[90:93], v114 offset:32768
	ds_read_b128 v[94:97], v118 offset:32768
	v_add3_u32 v122, 0, v84, v88
	v_add3_u32 v126, 0, v84, v86
	ds_read_b128 v[98:101], v122 offset:32768
	ds_read_b128 v[82:85], v126 offset:32768
	s_add_i32 s7, s12, 0xffffe000
	s_waitcnt lgkmcnt(3)
	v_mfma_f32_16x16x32_bf16 v[62:65], v[66:69], v[90:93], v[62:65]
	s_lshr_b32 s7, s7, 12
	s_add_i32 s7, s7, 1
	s_cmp_gt_i32 s22, 63
	v_mfma_f32_16x16x32_bf16 v[54:57], v[70:73], v[90:93], v[54:57]
	ds_read_b128 v[86:89], v0 offset:50176
	s_cselect_b32 s7, s7, 0
	s_mul_i32 s13, s62, 3
	v_mfma_f32_16x16x32_bf16 v[50:53], v[74:77], v[90:93], v[50:53]
	s_add_i32 s7, s7, s13
	s_mul_i32 s14, s7, 0x1800
	s_ashr_i32 s15, s14, 31
	v_mfma_f32_16x16x32_bf16 v[42:45], v[78:81], v[90:93], v[42:45]
	ds_read_b128 v[102:105], v0 offset:52224
	s_lshl_b64 s[14:15], s[14:15], 2
	s_add_u32 s7, s4, s14
	s_waitcnt lgkmcnt(4)
	v_mfma_f32_16x16x32_bf16 v[38:41], v[66:69], v[94:97], v[38:41]
	s_addc_u32 s13, s5, s15
	s_add_u32 s14, s7, 0x2000
	s_addc_u32 s15, s13, 0
	v_mfma_f32_16x16x32_bf16 v[34:37], v[70:73], v[94:97], v[34:37]
	ds_read_b128 v[106:109], v0 offset:54272
	s_add_i32 s21, s21, s83
	s_cmpk_gt_i32 s21, 0x7f
	v_mfma_f32_16x16x32_bf16 v[30:33], v[74:77], v[94:97], v[30:33]
	v_mfma_f32_16x16x32_bf16 v[26:29], v[78:81], v[94:97], v[26:29]
	ds_read_b128 v[110:113], v0 offset:56320
	v_mov_b32_e32 v0, v133
	s_waitcnt lgkmcnt(5)
	v_mfma_f32_16x16x32_bf16 v[22:25], v[66:69], v[98:101], v[22:25]
	v_mfma_f32_16x16x32_bf16 v[18:21], v[70:73], v[98:101], v[18:21]
	ds_read_b128 v[114:117], v114 offset:33792
	v_mfma_f32_16x16x32_bf16 v[14:17], v[74:77], v[98:101], v[14:17]
	v_mfma_f32_16x16x32_bf16 v[10:13], v[78:81], v[98:101], v[10:13]
	ds_read_b128 v[118:121], v118 offset:33792
	s_waitcnt lgkmcnt(6)
	v_mfma_f32_16x16x32_bf16 v[6:9], v[66:69], v[82:85], v[6:9]
	v_mfma_f32_16x16x32_bf16 v[2:5], v[70:73], v[82:85], v[2:5]
	ds_read_b128 v[122:125], v122 offset:33792
	v_mfma_f32_16x16x32_bf16 v[66:69], v[74:77], v[82:85], v[46:49]
	v_mfma_f32_16x16x32_bf16 v[70:73], v[78:81], v[82:85], v[58:61]
	ds_read_b128 v[126:129], v126 offset:33792
	s_waitcnt vmcnt(0)
	s_waitcnt lgkmcnt(0)
	v_mfma_f32_16x16x32_bf16 v[46:49], v[86:89], v[118:121], v[38:41]
	s_barrier
	v_mfma_f32_16x16x32_bf16 v[38:41], v[106:109], v[118:121], v[30:33]
	v_mfma_f32_16x16x32_bf16 v[30:33], v[86:89], v[122:125], v[22:25]
	v_mfma_f32_16x16x32_bf16 v[22:25], v[106:109], v[122:125], v[14:17]
	v_mfma_f32_16x16x32_bf16 v[14:17], v[86:89], v[126:129], v[6:9]
	v_mfma_f32_16x16x32_bf16 v[6:9], v[106:109], v[126:129], v[66:69]
	s_nop 2
	v_ashrrev_i32_e32 v66, 1, v0
	v_and_b32_e32 v66, 0xffffffc0, v66
	v_add_u32_e32 v66, s12, v66
	s_load_dwordx2 s[12:13], s[0:1], 0x128
	v_and_or_b32 v66, v0, 15, v66
	v_and_b32_e32 v67, 64, v0
	v_lshrrev_b32_e32 v0, 2, v0
	v_and_b32_e32 v0, 12, v0
	v_mfma_f32_16x16x32_bf16 v[58:61], v[102:105], v[114:117], v[54:57]
	v_mfma_f32_16x16x32_bf16 v[54:57], v[106:109], v[114:117], v[50:53]
	v_mfma_f32_16x16x32_bf16 v[50:53], v[110:113], v[114:117], v[42:45]
	v_mfma_f32_16x16x32_bf16 v[42:45], v[102:105], v[118:121], v[34:37]
	v_mfma_f32_16x16x32_bf16 v[34:37], v[110:113], v[118:121], v[26:29]
	v_mfma_f32_16x16x32_bf16 v[26:29], v[102:105], v[122:125], v[18:21]
	v_mfma_f32_16x16x32_bf16 v[18:21], v[110:113], v[122:125], v[10:13]
	v_mfma_f32_16x16x32_bf16 v[10:13], v[102:105], v[126:129], v[2:5]
	v_mfma_f32_16x16x32_bf16 v[2:5], v[110:113], v[126:129], v[70:73]
	s_nop 2
	v_or3_b32 v72, v67, v0, s6
	v_ashrrev_i32_e32 v67, 31, v66
	v_lshlrev_b64 v[68:69], 12, v[66:67]
	v_cmp_gt_i32_e64 s[6:7], s40, v66
	v_add_u32_e32 v0, 0xffffe000, v66
	s_waitcnt lgkmcnt(0)
	v_lshl_add_u64 v[74:75], s[12:13], 0, v[68:69]
	v_cndmask_b32_e64 v0, v0, v66, s[6:7]
	v_cndmask_b32_e64 v68, 0, v67, s[6:7]
	v_cndmask_b32_e64 v70, 8, 0, s[6:7]
	v_cndmask_b32_e32 v69, v67, v68, vcc
	v_cndmask_b32_e32 v68, v66, v0, vcc
	v_cndmask_b32_e32 v0, v186, v70, vcc
	v_lshl_add_u64 v[70:71], s[0:1], 0, v[0:1]
	global_load_dwordx2 v[70:71], v[70:71], off
	v_lshlrev_b64 v[68:69], 12, v[68:69]
	v_ashrrev_i32_e32 v73, 31, v72
	v_mfma_f32_16x16x32_bf16 v[62:65], v[86:89], v[114:117], v[62:65]
	v_add_u32_e32 v0, 0xffffe010, v66
	s_waitcnt vmcnt(0)
	v_lshl_add_u64 v[68:69], v[70:71], 0, v[68:69]
	v_lshlrev_b64 v[70:71], 2, v[72:73]
	v_lshl_add_u64 v[82:83], v[68:69], 0, v[70:71]
	v_lshl_add_u64 v[68:69], s[14:15], 0, v[70:71]
	v_lshl_add_u64 v[84:85], v[74:75], 0, v[70:71]
	global_load_dwordx4 v[74:77], v[82:83], off
	global_load_dwordx4 v[78:81], v[68:69], off
	s_waitcnt vmcnt(0)
	v_pk_fma_f32 v[62:63], v[62:63], v[78:79], v[74:75]
	v_pk_fma_f32 v[64:65], v[64:65], v[80:81], v[76:77]
	global_store_dwordx4 v[84:85], v[62:65], off
	global_load_dwordx4 v[74:77], v[82:83], off offset:64
	s_nop 0
	v_or_b32_e32 v62, 16, v72
	v_ashrrev_i32_e32 v63, 31, v62
	v_lshl_add_u64 v[62:63], v[62:63], 2, s[14:15]
	global_load_dwordx4 v[78:81], v[62:63], off
	s_waitcnt vmcnt(0)
	v_pk_fma_f32 v[58:59], v[58:59], v[78:79], v[74:75]
	v_pk_fma_f32 v[60:61], v[60:61], v[80:81], v[76:77]
	global_store_dwordx4 v[84:85], v[58:61], off offset:64
	global_load_dwordx4 v[74:77], v[82:83], off offset:128
	s_nop 0
	v_or_b32_e32 v58, 32, v72
	v_ashrrev_i32_e32 v59, 31, v58
	v_lshl_add_u64 v[58:59], v[58:59], 2, s[14:15]
	global_load_dwordx4 v[78:81], v[58:59], off
	s_waitcnt vmcnt(0)
	v_pk_fma_f32 v[54:55], v[54:55], v[78:79], v[74:75]
	v_pk_fma_f32 v[56:57], v[56:57], v[80:81], v[76:77]
	global_store_dwordx4 v[84:85], v[54:57], off offset:128
	s_nop 1
	v_or_b32_e32 v54, 48, v72
	v_ashrrev_i32_e32 v55, 31, v54
	v_lshl_add_u64 v[54:55], v[54:55], 2, s[14:15]
	global_load_dwordx4 v[72:75], v[82:83], off offset:192
	global_load_dwordx4 v[76:79], v[54:55], off
	s_waitcnt vmcnt(0)
	v_pk_fma_f32 v[50:51], v[50:51], v[76:77], v[72:73]
	v_pk_fma_f32 v[52:53], v[52:53], v[78:79], v[74:75]
	global_store_dwordx4 v[84:85], v[50:53], off offset:192
	global_load_dwordx4 v[72:75], v[68:69], off
	s_nop 0
	v_or_b32_e32 v50, 16, v66
	v_cmp_gt_i32_e64 s[6:7], s40, v50
	v_ashrrev_i32_e32 v51, 31, v50
	v_lshlrev_b64 v[52:53], 12, v[50:51]
	v_cndmask_b32_e64 v0, v0, v50, s[6:7]
	v_cndmask_b32_e64 v57, 8, 0, s[6:7]
	v_cndmask_b32_e64 v56, 0, v51, s[6:7]
	v_cndmask_b32_e32 v50, v50, v0, vcc
	v_cndmask_b32_e32 v0, v186, v57, vcc
	v_cndmask_b32_e32 v51, v51, v56, vcc
	v_lshl_add_u64 v[56:57], s[0:1], 0, v[0:1]
	global_load_dwordx2 v[56:57], v[56:57], off
	v_lshlrev_b64 v[50:51], 12, v[50:51]
	v_lshl_add_u64 v[52:53], s[12:13], 0, v[52:53]
	v_lshl_add_u64 v[60:61], v[52:53], 0, v[70:71]
	v_add_u32_e32 v0, 0xffffe020, v66
	s_waitcnt vmcnt(0)
	v_lshl_add_u64 v[50:51], v[56:57], 0, v[50:51]
	v_lshl_add_u64 v[56:57], v[50:51], 0, v[70:71]
	global_load_dwordx4 v[50:53], v[56:57], off
	s_waitcnt vmcnt(0)
	v_pk_fma_f32 v[46:47], v[46:47], v[72:73], v[50:51]
	v_pk_fma_f32 v[48:49], v[48:49], v[74:75], v[52:53]
	global_store_dwordx4 v[60:61], v[46:49], off
	global_load_dwordx4 v[46:49], v[56:57], off offset:64
	s_nop 0
	global_load_dwordx4 v[50:53], v[62:63], off
	s_waitcnt vmcnt(0)
	v_pk_fma_f32 v[42:43], v[42:43], v[50:51], v[46:47]
	v_pk_fma_f32 v[44:45], v[44:45], v[52:53], v[48:49]
	global_store_dwordx4 v[60:61], v[42:45], off offset:64
	global_load_dwordx4 v[42:45], v[56:57], off offset:128
	s_nop 0
	global_load_dwordx4 v[46:49], v[58:59], off
	s_waitcnt vmcnt(0)
	v_pk_fma_f32 v[38:39], v[38:39], v[46:47], v[42:43]
	v_pk_fma_f32 v[40:41], v[40:41], v[48:49], v[44:45]
	global_store_dwordx4 v[60:61], v[38:41], off offset:128
	global_load_dwordx4 v[38:41], v[56:57], off offset:192
	s_nop 0
	global_load_dwordx4 v[42:45], v[54:55], off
	s_waitcnt vmcnt(0)
	v_pk_fma_f32 v[34:35], v[34:35], v[42:43], v[38:39]
	v_pk_fma_f32 v[36:37], v[36:37], v[44:45], v[40:41]
	global_store_dwordx4 v[60:61], v[34:37], off offset:192
	s_nop 1
	v_or_b32_e32 v34, 32, v66
	v_cmp_gt_i32_e64 s[6:7], s40, v34
	v_ashrrev_i32_e32 v35, 31, v34
	v_lshlrev_b64 v[36:37], 12, v[34:35]
	v_cndmask_b32_e64 v0, v0, v34, s[6:7]
	v_cndmask_b32_e64 v39, 8, 0, s[6:7]
	v_cndmask_b32_e64 v38, 0, v35, s[6:7]
	v_cndmask_b32_e32 v34, v34, v0, vcc
	v_cndmask_b32_e32 v0, v186, v39, vcc
	v_cndmask_b32_e32 v35, v35, v38, vcc
	v_lshl_add_u64 v[38:39], s[0:1], 0, v[0:1]
	global_load_dwordx2 v[38:39], v[38:39], off
	v_lshlrev_b64 v[34:35], 12, v[34:35]
	v_lshl_add_u64 v[36:37], s[12:13], 0, v[36:37]
	v_lshl_add_u64 v[44:45], v[36:37], 0, v[70:71]
	v_add_u32_e32 v0, 0xffffe030, v66
	s_waitcnt vmcnt(0)
	v_lshl_add_u64 v[34:35], v[38:39], 0, v[34:35]
	v_lshl_add_u64 v[42:43], v[34:35], 0, v[70:71]
	global_load_dwordx4 v[34:37], v[42:43], off
	global_load_dwordx4 v[38:41], v[68:69], off
	s_waitcnt vmcnt(0)
	v_pk_fma_f32 v[30:31], v[30:31], v[38:39], v[34:35]
	v_pk_fma_f32 v[32:33], v[32:33], v[40:41], v[36:37]
	global_store_dwordx4 v[44:45], v[30:33], off
	global_load_dwordx4 v[30:33], v[42:43], off offset:64
	s_nop 0
	global_load_dwordx4 v[34:37], v[62:63], off
	s_waitcnt vmcnt(0)
	v_pk_fma_f32 v[26:27], v[26:27], v[34:35], v[30:31]
	v_pk_fma_f32 v[28:29], v[28:29], v[36:37], v[32:33]
	global_store_dwordx4 v[44:45], v[26:29], off offset:64
	global_load_dwordx4 v[26:29], v[42:43], off offset:128
	s_nop 0
	global_load_dwordx4 v[30:33], v[58:59], off
	s_waitcnt vmcnt(0)
	v_pk_fma_f32 v[22:23], v[22:23], v[30:31], v[26:27]
	v_pk_fma_f32 v[24:25], v[24:25], v[32:33], v[28:29]
	global_store_dwordx4 v[44:45], v[22:25], off offset:128
	global_load_dwordx4 v[22:25], v[42:43], off offset:192
	s_nop 0
	global_load_dwordx4 v[26:29], v[54:55], off
	s_waitcnt vmcnt(0)
	v_pk_fma_f32 v[18:19], v[18:19], v[26:27], v[22:23]
	v_pk_fma_f32 v[20:21], v[20:21], v[28:29], v[24:25]
	global_store_dwordx4 v[44:45], v[18:21], off offset:192
	s_nop 1
	v_or_b32_e32 v18, 48, v66
	v_cmp_gt_i32_e64 s[6:7], s40, v18
	v_ashrrev_i32_e32 v19, 31, v18
	v_lshlrev_b64 v[20:21], 12, v[18:19]
	v_cndmask_b32_e64 v0, v0, v18, s[6:7]
	v_cndmask_b32_e64 v23, 8, 0, s[6:7]
	v_cndmask_b32_e64 v22, 0, v19, s[6:7]
	v_cndmask_b32_e32 v18, v18, v0, vcc
	v_cndmask_b32_e32 v0, v186, v23, vcc
	v_cndmask_b32_e32 v19, v19, v22, vcc
	v_lshl_add_u64 v[22:23], s[0:1], 0, v[0:1]
	global_load_dwordx2 v[22:23], v[22:23], off
	v_lshlrev_b64 v[18:19], 12, v[18:19]
	v_lshl_add_u64 v[20:21], s[12:13], 0, v[20:21]
	v_lshl_add_u64 v[28:29], v[20:21], 0, v[70:71]
	s_waitcnt vmcnt(0)
	v_lshl_add_u64 v[18:19], v[22:23], 0, v[18:19]
	v_lshl_add_u64 v[26:27], v[18:19], 0, v[70:71]
	global_load_dwordx4 v[18:21], v[26:27], off
	global_load_dwordx4 v[22:25], v[68:69], off
	s_waitcnt vmcnt(0)
	v_pk_fma_f32 v[14:15], v[14:15], v[22:23], v[18:19]
	v_pk_fma_f32 v[16:17], v[16:17], v[24:25], v[20:21]
	global_store_dwordx4 v[28:29], v[14:17], off
	global_load_dwordx4 v[14:17], v[26:27], off offset:64
	s_nop 0
	global_load_dwordx4 v[18:21], v[62:63], off
	s_waitcnt vmcnt(0)
	v_pk_fma_f32 v[10:11], v[10:11], v[18:19], v[14:15]
	v_pk_fma_f32 v[12:13], v[12:13], v[20:21], v[16:17]
	global_store_dwordx4 v[28:29], v[10:13], off offset:64
	global_load_dwordx4 v[10:13], v[26:27], off offset:128
	s_nop 0
	global_load_dwordx4 v[14:17], v[58:59], off
	s_waitcnt vmcnt(0)
	v_pk_fma_f32 v[6:7], v[6:7], v[14:15], v[10:11]
	v_pk_fma_f32 v[8:9], v[8:9], v[16:17], v[12:13]
	global_store_dwordx4 v[28:29], v[6:9], off offset:128
	global_load_dwordx4 v[6:9], v[26:27], off offset:192
	s_nop 0
	global_load_dwordx4 v[10:13], v[54:55], off
	s_waitcnt vmcnt(0)
	v_pk_fma_f32 v[2:3], v[2:3], v[10:11], v[6:7]
	v_pk_fma_f32 v[4:5], v[4:5], v[12:13], v[8:9]
	global_store_dwordx4 v[28:29], v[2:5], off offset:192
	s_cbranch_scc0 .LBB0_63

.LBB0_809:
	s_mul_hi_i32 s6, s21, 0x92492493
	s_add_i32 s6, s6, s21
	s_lshr_b32 s7, s6, 31
	s_ashr_i32 s6, s6, 5
	s_add_i32 s6, s6, s7
	s_lshl_b32 s7, s6, 3
	s_or_b32 s7, s7, s65
	s_mul_hi_i32 s8, s7, 0x55555556
	s_lshr_b32 s9, s8, 31
	s_add_i32 s8, s8, s9
	s_mul_i32 s6, s6, 56
	s_mul_i32 s9, s8, 3
	s_sub_i32 s6, s21, s6
	s_sub_i32 s7, s7, s9
	s_bfe_i32 s9, s6, 0x80000
	s_mul_i32 s9, s9, 0xff93
	s_bfe_u32 s9, s9, 0x80008
	s_add_i32 s9, s9, s6
	s_bfe_i32 s10, s9, 0x80000
	s_sext_i32_i16 s10, s10
	s_ashr_i32 s10, s10, 2
	s_bfe_u32 s9, s9, 0x10007
	s_add_i32 s9, s10, s9
	s_mul_i32 s10, s9, 7
	s_sub_i32 s6, s6, s10
	s_mul_i32 s7, s7, 7
	s_sext_i32_i8 s6, s6
	s_add_i32 s7, s7, s6
	s_sext_i32_i16 s6, s9
	s_lshl_b32 s8, s8, 10
	s_lshl_b32 s6, s6, 7
	v_mov_b32_e32 v26, v133
	s_add_i32 s6, s8, s6
	s_lshl_b32 s8, s7, 7
	v_lshlrev_b32_e32 v16, 4, v26
	v_and_b32_e32 v0, 32, v26
	s_ashr_i32 s7, s6, 31
	v_bitop3_b32 v0, v16, v0, 48 bitop3:0x6c
	s_lshl_b64 s[16:17], s[6:7], 11
	v_lshrrev_b32_e32 v17, 2, v26
	v_lshrrev_b32_e32 v2, 1, v26
	v_lshrrev_b32_e32 v0, 1, v0
	v_ashrrev_i32_e32 v4, 3, v26
	s_add_u32 s22, s3, s16
	v_and_b32_e32 v27, 0xfffffc00, v16
	v_and_or_b32 v0, v2, 32, v0
	v_bfi_b32 v4, -16, v4, v17
	s_addc_u32 s23, s18, s17
	v_lshlrev_b32_e32 v0, 1, v0
	v_ashrrev_i32_e32 v5, 31, v4
	v_add_u32_e32 v8, 0x1000, v16
	v_add_u32_e32 v82, 0, v27
	v_lshl_add_u64 v[2:3], s[22:23], 0, v[0:1]
	v_lshlrev_b64 v[4:5], 11, v[4:5]
	v_ashrrev_i32_e32 v8, 7, v8
	v_add_u32_e32 v12, 0x2000, v16
	v_readfirstlane_b32 s7, v82
	v_lshl_add_u64 v[6:7], v[2:3], 0, v[4:5]
	v_bfi_b32 v8, -16, v8, v17
	v_ashrrev_i32_e32 v12, 7, v12
	v_add_u32_e32 v16, 0x3000, v16
	s_mov_b32 m0, s7
	v_ashrrev_i32_e32 v9, 31, v8
	v_bfi_b32 v12, -16, v12, v17
	v_ashrrev_i32_e32 v16, 7, v16
	s_barrier
	global_load_lds_dwordx4 v[6:7], off
	v_add_u32_e32 v6, 0x1000, v82
	v_lshlrev_b64 v[8:9], 11, v[8:9]
	v_ashrrev_i32_e32 v13, 31, v12
	v_bfi_b32 v16, -16, v16, v17
	v_readfirstlane_b32 s7, v6
	v_add_u32_e32 v6, 0x2000, v82
	s_ashr_i32 s9, s8, 31
	v_lshl_add_u64 v[10:11], v[2:3], 0, v[8:9]
	v_lshlrev_b64 v[12:13], 11, v[12:13]
	v_ashrrev_i32_e32 v17, 31, v16
	s_mov_b32 m0, s7
	v_readfirstlane_b32 s7, v6
	v_add_u32_e32 v6, 0x3000, v82
	s_lshl_b64 s[10:11], s[8:9], 11
	v_lshl_add_u64 v[14:15], v[2:3], 0, v[12:13]
	v_lshlrev_b64 v[16:17], 11, v[16:17]
	global_load_lds_dwordx4 v[10:11], off
	s_mov_b32 m0, s7
	v_readfirstlane_b32 s7, v6
	s_add_u32 s24, s19, s10
	v_lshl_add_u64 v[2:3], v[2:3], 0, v[16:17]
	global_load_lds_dwordx4 v[14:15], off
	s_mov_b32 m0, s7
	s_addc_u32 s25, s20, s11
	global_load_lds_dwordx4 v[2:3], off
	v_add_u32_e32 v2, 0x4000, v82
	v_lshl_add_u64 v[18:19], s[24:25], 0, v[0:1]
	v_readfirstlane_b32 s7, v2
	v_add_u32_e32 v2, 0x5000, v82
	v_lshl_add_u64 v[20:21], v[18:19], 0, v[4:5]
	s_mov_b32 m0, s7
	v_readfirstlane_b32 s7, v2
	v_add_u32_e32 v2, 0x6000, v82
	v_lshl_add_u64 v[22:23], v[18:19], 0, v[8:9]
	global_load_lds_dwordx4 v[20:21], off
	s_mov_b32 m0, s7
	v_readfirstlane_b32 s7, v2
	v_add_u32_e32 v2, 0x7000, v82
	v_lshl_add_u64 v[24:25], v[18:19], 0, v[12:13]
	global_load_lds_dwordx4 v[22:23], off
	s_mov_b32 m0, s7
	v_readfirstlane_b32 s7, v2
	v_lshl_add_u64 v[18:19], v[18:19], 0, v[16:17]
	global_load_lds_dwordx4 v[24:25], off
	s_mov_b32 m0, s7
	v_and_b32_e32 v2, 15, v26
	global_load_lds_dwordx4 v[18:19], off
	v_lshlrev_b32_e32 v6, 2, v26
	v_and_b32_e32 v3, 48, v26
	v_lshlrev_b32_e32 v2, 6, v2
	v_and_b32_e32 v6, 32, v6
	v_bitop3_b32 v83, v2, v6, v3 bitop3:0x36
	v_lshlrev_b32_e32 v2, 7, v26
	v_and_b32_e32 v89, 0x2000, v2
	v_lshlrev_b32_e32 v2, 6, v26
	v_and_b32_e32 v87, 0xffffe000, v2
	v_and_b32_e32 v2, 0x3c0, v2
	v_bitop3_b32 v84, v2, v6, v3 bitop3:0x36
	v_lshl_add_u64 v[2:3], s[16:17], 0, v[4:5]
	v_or_b32_e32 v2, v2, v0
	v_lshl_add_u64 v[66:67], s[12:13], 0, v[2:3]
	v_lshl_add_u64 v[2:3], s[16:17], 0, v[8:9]
	v_or_b32_e32 v2, v2, v0
	v_lshl_add_u64 v[68:69], s[12:13], 0, v[2:3]
	v_lshl_add_u64 v[2:3], s[16:17], 0, v[12:13]
	v_or_b32_e32 v2, v2, v0
	v_lshl_add_u64 v[70:71], s[12:13], 0, v[2:3]
	v_lshl_add_u64 v[2:3], s[16:17], 0, v[16:17]
	v_or_b32_e32 v2, v2, v0
	v_lshl_add_u64 v[72:73], s[12:13], 0, v[2:3]
	v_lshl_add_u64 v[2:3], s[10:11], 0, v[4:5]
	v_or_b32_e32 v2, v2, v0
	v_lshl_add_u64 v[74:75], s[14:15], 0, v[2:3]
	v_lshl_add_u64 v[2:3], s[10:11], 0, v[8:9]
	v_or_b32_e32 v2, v2, v0
	v_lshl_add_u64 v[76:77], s[14:15], 0, v[2:3]
	v_lshl_add_u64 v[2:3], s[10:11], 0, v[12:13]
	v_or_b32_e32 v2, v2, v0
	s_waitcnt vmcnt(0)
	v_lshl_add_u64 v[78:79], s[14:15], 0, v[2:3]
	v_lshl_add_u64 v[2:3], s[10:11], 0, v[16:17]
	v_or_b32_e32 v2, v2, v0
	v_mov_b32_e32 v62, 0
	v_or_b32_e32 v85, 0x800, v87
	v_or_b32_e32 v88, 0x1000, v87
	v_or_b32_e32 v86, 0x1800, v87
	v_lshl_add_u64 v[80:81], s[14:15], 0, v[2:3]
	s_mov_b64 s[10:11], 0
	s_mov_b32 s7, 0
	v_mov_b32_e32 v63, v62
	v_mov_b32_e32 v64, v62
	v_mov_b32_e32 v65, v62
	v_mov_b32_e32 v58, v62
	v_mov_b32_e32 v59, v62
	v_mov_b32_e32 v60, v62
	v_mov_b32_e32 v61, v62
	v_mov_b32_e32 v2, v62
	v_mov_b32_e32 v3, v62
	v_mov_b32_e32 v4, v62
	v_mov_b32_e32 v5, v62
	v_mov_b32_e32 v6, v62
	v_mov_b32_e32 v7, v62
	v_mov_b32_e32 v8, v62
	v_mov_b32_e32 v9, v62
	v_mov_b32_e32 v10, v62
	v_mov_b32_e32 v11, v62
	v_mov_b32_e32 v12, v62
	v_mov_b32_e32 v13, v62
	v_mov_b32_e32 v14, v62
	v_mov_b32_e32 v15, v62
	v_mov_b32_e32 v16, v62
	v_mov_b32_e32 v17, v62
	v_mov_b32_e32 v18, v62
	v_mov_b32_e32 v19, v62
	v_mov_b32_e32 v20, v62
	v_mov_b32_e32 v21, v62
	v_mov_b32_e32 v22, v62
	v_mov_b32_e32 v23, v62
	v_mov_b32_e32 v24, v62
	v_mov_b32_e32 v25, v62
	v_mov_b32_e32 v26, v62
	v_mov_b32_e32 v27, v62
	v_mov_b32_e32 v28, v62
	v_mov_b32_e32 v29, v62
	v_mov_b32_e32 v30, v62
	v_mov_b32_e32 v31, v62
	v_mov_b32_e32 v32, v62
	v_mov_b32_e32 v33, v62
	v_mov_b32_e32 v34, v62
	v_mov_b32_e32 v35, v62
	v_mov_b32_e32 v36, v62
	v_mov_b32_e32 v37, v62
	v_mov_b32_e32 v38, v62
	v_mov_b32_e32 v39, v62
	v_mov_b32_e32 v40, v62
	v_mov_b32_e32 v41, v62
	v_mov_b32_e32 v42, v62
	v_mov_b32_e32 v43, v62
	v_mov_b32_e32 v44, v62
	v_mov_b32_e32 v45, v62
	v_mov_b32_e32 v46, v62
	v_mov_b32_e32 v47, v62
	v_mov_b32_e32 v48, v62
	v_mov_b32_e32 v49, v62
	v_mov_b32_e32 v50, v62
	v_mov_b32_e32 v51, v62
	v_mov_b32_e32 v52, v62
	v_mov_b32_e32 v53, v62
	v_mov_b32_e32 v54, v62
	v_mov_b32_e32 v55, v62
	v_mov_b32_e32 v56, v62
	v_mov_b32_e32 v57, v62
	s_waitcnt vmcnt(0) lgkmcnt(0)
	s_barrier
	v_readfirstlane_b32 s9, v82
	v_add_u32_e32 v141, v83, v87
	v_add_u32_e32 v142, v83, v89
	ds_read_b128 v[90:93], v142 offset:16384
	ds_read_b128 v[94:97], v142 offset:18432
	ds_read_b128 v[98:101], v142 offset:20480
	ds_read_b128 v[102:105], v142 offset:22528
	ds_read_b128 v[106:109], v141
	ds_read_b128 v[110:113], v141 offset:2048
	ds_read_b128 v[114:117], v141 offset:4096
	ds_read_b128 v[118:121], v141 offset:6144
	s_add_u32 m0, s9, 0x8000
	v_lshl_add_u64 v[176:177], v[66:67], 0, s[10:11]
	global_load_lds_dwordx4 v[176:177], off
	s_add_u32 m0, s9, 0x9000
	v_lshl_add_u64 v[178:179], v[68:69], 0, s[10:11]
	global_load_lds_dwordx4 v[178:179], off
	s_add_u32 m0, s9, 0xa000
	v_lshl_add_u64 v[176:177], v[70:71], 0, s[10:11]
	global_load_lds_dwordx4 v[176:177], off
	s_add_u32 m0, s9, 0xb000
	v_lshl_add_u64 v[178:179], v[72:73], 0, s[10:11]
	global_load_lds_dwordx4 v[178:179], off
	s_add_u32 m0, s9, 0xc000
	v_lshl_add_u64 v[176:177], v[74:75], 0, s[10:11]
	global_load_lds_dwordx4 v[176:177], off
	s_add_u32 m0, s9, 0xd000
	v_lshl_add_u64 v[178:179], v[76:77], 0, s[10:11]
	global_load_lds_dwordx4 v[178:179], off
	s_add_u32 m0, s9, 0xe000
	v_lshl_add_u64 v[176:177], v[78:79], 0, s[10:11]
	global_load_lds_dwordx4 v[176:177], off
	s_add_u32 m0, s9, 0xf000
	v_lshl_add_u64 v[178:179], v[80:81], 0, s[10:11]
	global_load_lds_dwordx4 v[178:179], off
	s_add_u32 s10, s10, 0x80
	s_addc_u32 s11, s11, 0
	s_mov_b32 s16, 7
.Lgp_i810_loop:
	s_waitcnt lgkmcnt(0)
	v_mfma_f32_16x16x32_bf16 v[54:57], v[90:93], v[106:109], v[54:57]
	ds_read_b128 v[144:147], v142 offset:17408
	v_mfma_f32_16x16x32_bf16 v[50:53], v[94:97], v[106:109], v[50:53]
	ds_read_b128 v[148:151], v142 offset:19456
	v_mfma_f32_16x16x32_bf16 v[46:49], v[98:101], v[106:109], v[46:49]
	ds_read_b128 v[152:155], v142 offset:21504
	v_mfma_f32_16x16x32_bf16 v[42:45], v[102:105], v[106:109], v[42:45]
	ds_read_b128 v[156:159], v142 offset:23552
	v_mfma_f32_16x16x32_bf16 v[38:41], v[90:93], v[110:113], v[38:41]
	ds_read_b128 v[160:163], v141 offset:1024
	v_mfma_f32_16x16x32_bf16 v[34:37], v[94:97], v[110:113], v[34:37]
	ds_read_b128 v[164:167], v141 offset:3072
	v_mfma_f32_16x16x32_bf16 v[30:33], v[98:101], v[110:113], v[30:33]
	ds_read_b128 v[168:171], v141 offset:5120
	v_mfma_f32_16x16x32_bf16 v[26:29], v[102:105], v[110:113], v[26:29]
	ds_read_b128 v[172:175], v141 offset:7168
	v_mfma_f32_16x16x32_bf16 v[22:25], v[90:93], v[114:117], v[22:25]
	v_mfma_f32_16x16x32_bf16 v[18:21], v[94:97], v[114:117], v[18:21]
	v_mfma_f32_16x16x32_bf16 v[14:17], v[98:101], v[114:117], v[14:17]
	v_mfma_f32_16x16x32_bf16 v[10:13], v[102:105], v[114:117], v[10:13]
	v_mfma_f32_16x16x32_bf16 v[6:9], v[90:93], v[118:121], v[6:9]
	v_mfma_f32_16x16x32_bf16 v[2:5], v[94:97], v[118:121], v[2:5]
	v_mfma_f32_16x16x32_bf16 v[58:61], v[98:101], v[118:121], v[58:61]
	v_mfma_f32_16x16x32_bf16 v[62:65], v[102:105], v[118:121], v[62:65]
	s_waitcnt vmcnt(0) lgkmcnt(0)
	s_barrier
	v_mfma_f32_16x16x32_bf16 v[54:57], v[144:147], v[160:163], v[54:57]
	ds_read_b128 v[90:93], v142 offset:49152
	s_add_u32 m0, s9, 0x0
	v_lshl_add_u64 v[176:177], v[66:67], 0, s[10:11]
	global_load_lds_dwordx4 v[176:177], off
	v_mfma_f32_16x16x32_bf16 v[50:53], v[148:151], v[160:163], v[50:53]
	ds_read_b128 v[94:97], v142 offset:51200
	s_add_u32 m0, s9, 0x1000
	v_lshl_add_u64 v[178:179], v[68:69], 0, s[10:11]
	global_load_lds_dwordx4 v[178:179], off
	v_mfma_f32_16x16x32_bf16 v[46:49], v[152:155], v[160:163], v[46:49]
	ds_read_b128 v[98:101], v142 offset:53248
	s_add_u32 m0, s9, 0x2000
	v_lshl_add_u64 v[176:177], v[70:71], 0, s[10:11]
	global_load_lds_dwordx4 v[176:177], off
	v_mfma_f32_16x16x32_bf16 v[42:45], v[156:159], v[160:163], v[42:45]
	ds_read_b128 v[102:105], v142 offset:55296
	s_add_u32 m0, s9, 0x3000
	v_lshl_add_u64 v[178:179], v[72:73], 0, s[10:11]
	global_load_lds_dwordx4 v[178:179], off
	v_mfma_f32_16x16x32_bf16 v[38:41], v[144:147], v[164:167], v[38:41]
	ds_read_b128 v[106:109], v141 offset:32768
	s_add_u32 m0, s9, 0x4000
	v_lshl_add_u64 v[176:177], v[74:75], 0, s[10:11]
	global_load_lds_dwordx4 v[176:177], off
	v_mfma_f32_16x16x32_bf16 v[34:37], v[148:151], v[164:167], v[34:37]
	ds_read_b128 v[110:113], v141 offset:34816
	s_add_u32 m0, s9, 0x5000
	v_lshl_add_u64 v[178:179], v[76:77], 0, s[10:11]
	global_load_lds_dwordx4 v[178:179], off
	v_mfma_f32_16x16x32_bf16 v[30:33], v[152:155], v[164:167], v[30:33]
	ds_read_b128 v[114:117], v141 offset:36864
	s_add_u32 m0, s9, 0x6000
	v_lshl_add_u64 v[176:177], v[78:79], 0, s[10:11]
	global_load_lds_dwordx4 v[176:177], off
	v_mfma_f32_16x16x32_bf16 v[26:29], v[156:159], v[164:167], v[26:29]
	ds_read_b128 v[118:121], v141 offset:38912
	s_add_u32 m0, s9, 0x7000
	v_lshl_add_u64 v[178:179], v[80:81], 0, s[10:11]
	global_load_lds_dwordx4 v[178:179], off
	v_mfma_f32_16x16x32_bf16 v[22:25], v[144:147], v[168:171], v[22:25]
	v_mfma_f32_16x16x32_bf16 v[18:21], v[148:151], v[168:171], v[18:21]
	v_mfma_f32_16x16x32_bf16 v[14:17], v[152:155], v[168:171], v[14:17]
	v_mfma_f32_16x16x32_bf16 v[10:13], v[156:159], v[168:171], v[10:13]
	v_mfma_f32_16x16x32_bf16 v[6:9], v[144:147], v[172:175], v[6:9]
	v_mfma_f32_16x16x32_bf16 v[2:5], v[148:151], v[172:175], v[2:5]
	v_mfma_f32_16x16x32_bf16 v[58:61], v[152:155], v[172:175], v[58:61]
	v_mfma_f32_16x16x32_bf16 v[62:65], v[156:159], v[172:175], v[62:65]
	s_add_u32 s10, s10, 0x80
	s_addc_u32 s11, s11, 0
	s_waitcnt lgkmcnt(0)
	v_mfma_f32_16x16x32_bf16 v[54:57], v[90:93], v[106:109], v[54:57]
	ds_read_b128 v[144:147], v142 offset:50176
	v_mfma_f32_16x16x32_bf16 v[50:53], v[94:97], v[106:109], v[50:53]
	ds_read_b128 v[148:151], v142 offset:52224
	v_mfma_f32_16x16x32_bf16 v[46:49], v[98:101], v[106:109], v[46:49]
	ds_read_b128 v[152:155], v142 offset:54272
	v_mfma_f32_16x16x32_bf16 v[42:45], v[102:105], v[106:109], v[42:45]
	ds_read_b128 v[156:159], v142 offset:56320
	v_mfma_f32_16x16x32_bf16 v[38:41], v[90:93], v[110:113], v[38:41]
	ds_read_b128 v[160:163], v141 offset:33792
	v_mfma_f32_16x16x32_bf16 v[34:37], v[94:97], v[110:113], v[34:37]
	ds_read_b128 v[164:167], v141 offset:35840
	v_mfma_f32_16x16x32_bf16 v[30:33], v[98:101], v[110:113], v[30:33]
	ds_read_b128 v[168:171], v141 offset:37888
	v_mfma_f32_16x16x32_bf16 v[26:29], v[102:105], v[110:113], v[26:29]
	ds_read_b128 v[172:175], v141 offset:39936
	v_mfma_f32_16x16x32_bf16 v[22:25], v[90:93], v[114:117], v[22:25]
	v_mfma_f32_16x16x32_bf16 v[18:21], v[94:97], v[114:117], v[18:21]
	v_mfma_f32_16x16x32_bf16 v[14:17], v[98:101], v[114:117], v[14:17]
	v_mfma_f32_16x16x32_bf16 v[10:13], v[102:105], v[114:117], v[10:13]
	v_mfma_f32_16x16x32_bf16 v[6:9], v[90:93], v[118:121], v[6:9]
	v_mfma_f32_16x16x32_bf16 v[2:5], v[94:97], v[118:121], v[2:5]
	v_mfma_f32_16x16x32_bf16 v[58:61], v[98:101], v[118:121], v[58:61]
	v_mfma_f32_16x16x32_bf16 v[62:65], v[102:105], v[118:121], v[62:65]
	s_waitcnt vmcnt(0) lgkmcnt(0)
	s_barrier
	v_mfma_f32_16x16x32_bf16 v[54:57], v[144:147], v[160:163], v[54:57]
	ds_read_b128 v[90:93], v142 offset:16384
	s_add_u32 m0, s9, 0x8000
	v_lshl_add_u64 v[176:177], v[66:67], 0, s[10:11]
	global_load_lds_dwordx4 v[176:177], off
	v_mfma_f32_16x16x32_bf16 v[50:53], v[148:151], v[160:163], v[50:53]
	ds_read_b128 v[94:97], v142 offset:18432
	s_add_u32 m0, s9, 0x9000
	v_lshl_add_u64 v[178:179], v[68:69], 0, s[10:11]
	global_load_lds_dwordx4 v[178:179], off
	v_mfma_f32_16x16x32_bf16 v[46:49], v[152:155], v[160:163], v[46:49]
	ds_read_b128 v[98:101], v142 offset:20480
	s_add_u32 m0, s9, 0xa000
	v_lshl_add_u64 v[176:177], v[70:71], 0, s[10:11]
	global_load_lds_dwordx4 v[176:177], off
	v_mfma_f32_16x16x32_bf16 v[42:45], v[156:159], v[160:163], v[42:45]
	ds_read_b128 v[102:105], v142 offset:22528
	s_add_u32 m0, s9, 0xb000
	v_lshl_add_u64 v[178:179], v[72:73], 0, s[10:11]
	global_load_lds_dwordx4 v[178:179], off
	v_mfma_f32_16x16x32_bf16 v[38:41], v[144:147], v[164:167], v[38:41]
	ds_read_b128 v[106:109], v141
	s_add_u32 m0, s9, 0xc000
	v_lshl_add_u64 v[176:177], v[74:75], 0, s[10:11]
	global_load_lds_dwordx4 v[176:177], off
	v_mfma_f32_16x16x32_bf16 v[34:37], v[148:151], v[164:167], v[34:37]
	ds_read_b128 v[110:113], v141 offset:2048
	s_add_u32 m0, s9, 0xd000
	v_lshl_add_u64 v[178:179], v[76:77], 0, s[10:11]
	global_load_lds_dwordx4 v[178:179], off
	v_mfma_f32_16x16x32_bf16 v[30:33], v[152:155], v[164:167], v[30:33]
	ds_read_b128 v[114:117], v141 offset:4096
	s_add_u32 m0, s9, 0xe000
	v_lshl_add_u64 v[176:177], v[78:79], 0, s[10:11]
	global_load_lds_dwordx4 v[176:177], off
	v_mfma_f32_16x16x32_bf16 v[26:29], v[156:159], v[164:167], v[26:29]
	ds_read_b128 v[118:121], v141 offset:6144
	s_add_u32 m0, s9, 0xf000
	v_lshl_add_u64 v[178:179], v[80:81], 0, s[10:11]
	global_load_lds_dwordx4 v[178:179], off
	v_mfma_f32_16x16x32_bf16 v[22:25], v[144:147], v[168:171], v[22:25]
	v_mfma_f32_16x16x32_bf16 v[18:21], v[148:151], v[168:171], v[18:21]
	v_mfma_f32_16x16x32_bf16 v[14:17], v[152:155], v[168:171], v[14:17]
	v_mfma_f32_16x16x32_bf16 v[10:13], v[156:159], v[168:171], v[10:13]
	v_mfma_f32_16x16x32_bf16 v[6:9], v[144:147], v[172:175], v[6:9]
	v_mfma_f32_16x16x32_bf16 v[2:5], v[148:151], v[172:175], v[2:5]
	v_mfma_f32_16x16x32_bf16 v[58:61], v[152:155], v[172:175], v[58:61]
	v_mfma_f32_16x16x32_bf16 v[62:65], v[156:159], v[172:175], v[62:65]
	s_add_u32 s10, s10, 0x80
	s_addc_u32 s11, s11, 0
	s_sub_u32 s16, s16, 1
	s_cmp_lg_u32 s16, 0
	s_cbranch_scc1 .Lgp_i810_loop
	s_waitcnt lgkmcnt(0)
	v_mfma_f32_16x16x32_bf16 v[54:57], v[90:93], v[106:109], v[54:57]
	ds_read_b128 v[144:147], v142 offset:17408
	v_mfma_f32_16x16x32_bf16 v[50:53], v[94:97], v[106:109], v[50:53]
	ds_read_b128 v[148:151], v142 offset:19456
	v_mfma_f32_16x16x32_bf16 v[46:49], v[98:101], v[106:109], v[46:49]
	ds_read_b128 v[152:155], v142 offset:21504
	v_mfma_f32_16x16x32_bf16 v[42:45], v[102:105], v[106:109], v[42:45]
	ds_read_b128 v[156:159], v142 offset:23552
	v_mfma_f32_16x16x32_bf16 v[38:41], v[90:93], v[110:113], v[38:41]
	ds_read_b128 v[160:163], v141 offset:1024
	v_mfma_f32_16x16x32_bf16 v[34:37], v[94:97], v[110:113], v[34:37]
	ds_read_b128 v[164:167], v141 offset:3072
	v_mfma_f32_16x16x32_bf16 v[30:33], v[98:101], v[110:113], v[30:33]
	ds_read_b128 v[168:171], v141 offset:5120
	v_mfma_f32_16x16x32_bf16 v[26:29], v[102:105], v[110:113], v[26:29]
	ds_read_b128 v[172:175], v141 offset:7168
	v_mfma_f32_16x16x32_bf16 v[22:25], v[90:93], v[114:117], v[22:25]
	v_mfma_f32_16x16x32_bf16 v[18:21], v[94:97], v[114:117], v[18:21]
	v_mfma_f32_16x16x32_bf16 v[14:17], v[98:101], v[114:117], v[14:17]
	v_mfma_f32_16x16x32_bf16 v[10:13], v[102:105], v[114:117], v[10:13]
	v_mfma_f32_16x16x32_bf16 v[6:9], v[90:93], v[118:121], v[6:9]
	v_mfma_f32_16x16x32_bf16 v[2:5], v[94:97], v[118:121], v[2:5]
	v_mfma_f32_16x16x32_bf16 v[58:61], v[98:101], v[118:121], v[58:61]
	v_mfma_f32_16x16x32_bf16 v[62:65], v[102:105], v[118:121], v[62:65]
	s_waitcnt vmcnt(0) lgkmcnt(0)
	s_barrier
	v_mfma_f32_16x16x32_bf16 v[54:57], v[144:147], v[160:163], v[54:57]
	v_mfma_f32_16x16x32_bf16 v[50:53], v[148:151], v[160:163], v[50:53]
	v_mfma_f32_16x16x32_bf16 v[46:49], v[152:155], v[160:163], v[46:49]
	v_mfma_f32_16x16x32_bf16 v[42:45], v[156:159], v[160:163], v[42:45]
	v_mfma_f32_16x16x32_bf16 v[38:41], v[144:147], v[164:167], v[38:41]
	v_mfma_f32_16x16x32_bf16 v[34:37], v[148:151], v[164:167], v[34:37]
	v_mfma_f32_16x16x32_bf16 v[30:33], v[152:155], v[164:167], v[30:33]
	v_mfma_f32_16x16x32_bf16 v[26:29], v[156:159], v[164:167], v[26:29]
	v_mfma_f32_16x16x32_bf16 v[22:25], v[144:147], v[168:171], v[22:25]
	v_mfma_f32_16x16x32_bf16 v[18:21], v[148:151], v[168:171], v[18:21]
	v_mfma_f32_16x16x32_bf16 v[14:17], v[152:155], v[168:171], v[14:17]
	v_mfma_f32_16x16x32_bf16 v[10:13], v[156:159], v[168:171], v[10:13]
	v_mfma_f32_16x16x32_bf16 v[6:9], v[144:147], v[172:175], v[6:9]
	v_mfma_f32_16x16x32_bf16 v[2:5], v[148:151], v[172:175], v[2:5]
	v_mfma_f32_16x16x32_bf16 v[58:61], v[152:155], v[172:175], v[58:61]
	v_mfma_f32_16x16x32_bf16 v[62:65], v[156:159], v[172:175], v[62:65]
	v_add3_u32 v0, 0, v83, v89
	ds_read_b128 v[66:69], v0 offset:49152
	ds_read_b128 v[70:73], v0 offset:51200
	ds_read_b128 v[74:77], v0 offset:53248
	ds_read_b128 v[78:81], v0 offset:55296
	v_add3_u32 v106, 0, v83, v87
	v_add3_u32 v110, 0, v84, v85
	ds_read_b128 v[90:93], v106 offset:32768
	ds_read_b128 v[94:97], v110 offset:32768
	v_add3_u32 v111, 0, v84, v88
	v_add3_u32 v112, 0, v84, v86
	ds_read_b128 v[98:101], v111 offset:32768
	ds_read_b128 v[82:85], v112 offset:32768
	s_waitcnt lgkmcnt(3)
	v_mfma_f32_16x16x32_bf16 v[54:57], v[66:69], v[90:93], v[54:57]
	v_mfma_f32_16x16x32_bf16 v[50:53], v[70:73], v[90:93], v[50:53]
	ds_read_b128 v[86:89], v0 offset:50176
	v_mfma_f32_16x16x32_bf16 v[46:49], v[74:77], v[90:93], v[46:49]
	v_mfma_f32_16x16x32_bf16 v[42:45], v[78:81], v[90:93], v[42:45]
	ds_read_b128 v[90:93], v0 offset:52224
	s_waitcnt lgkmcnt(4)
	v_mfma_f32_16x16x32_bf16 v[38:41], v[66:69], v[94:97], v[38:41]
	v_mfma_f32_16x16x32_bf16 v[34:37], v[70:73], v[94:97], v[34:37]
	ds_read_b128 v[102:105], v0 offset:54272
	v_mfma_f32_16x16x32_bf16 v[30:33], v[74:77], v[94:97], v[30:33]
	v_mfma_f32_16x16x32_bf16 v[26:29], v[78:81], v[94:97], v[26:29]
	ds_read_b128 v[94:97], v0 offset:56320
	v_mov_b32_e32 v0, v133
	s_waitcnt lgkmcnt(5)
	v_mfma_f32_16x16x32_bf16 v[22:25], v[66:69], v[98:101], v[22:25]
	v_mfma_f32_16x16x32_bf16 v[18:21], v[70:73], v[98:101], v[18:21]
	ds_read_b128 v[106:109], v106 offset:33792
	v_mfma_f32_16x16x32_bf16 v[14:17], v[74:77], v[98:101], v[14:17]
	v_mfma_f32_16x16x32_bf16 v[10:13], v[78:81], v[98:101], v[10:13]
	ds_read_b128 v[98:101], v110 offset:33792
	s_waitcnt lgkmcnt(6)
	v_mfma_f32_16x16x32_bf16 v[6:9], v[66:69], v[82:85], v[6:9]
	v_mfma_f32_16x16x32_bf16 v[2:5], v[70:73], v[82:85], v[2:5]
	ds_read_b128 v[66:69], v111 offset:33792
	v_mfma_f32_16x16x32_bf16 v[70:73], v[74:77], v[82:85], v[58:61]
	v_mfma_f32_16x16x32_bf16 v[74:77], v[78:81], v[82:85], v[62:65]
	ds_read_b128 v[78:81], v112 offset:33792
	s_waitcnt vmcnt(0)
	s_waitcnt lgkmcnt(0)
	v_mfma_f32_16x16x32_bf16 v[62:65], v[86:89], v[106:109], v[54:57]
	s_barrier
	v_mfma_f32_16x16x32_bf16 v[58:61], v[90:93], v[106:109], v[50:53]
	v_mfma_f32_16x16x32_bf16 v[54:57], v[102:105], v[106:109], v[46:49]
	v_mfma_f32_16x16x32_bf16 v[50:53], v[94:97], v[106:109], v[42:45]
	v_mfma_f32_16x16x32_bf16 v[46:49], v[86:89], v[98:101], v[38:41]
	v_mfma_f32_16x16x32_bf16 v[42:45], v[90:93], v[98:101], v[34:37]
	v_mfma_f32_16x16x32_bf16 v[38:41], v[102:105], v[98:101], v[30:33]
	v_mfma_f32_16x16x32_bf16 v[34:37], v[94:97], v[98:101], v[26:29]
	v_mfma_f32_16x16x32_bf16 v[30:33], v[86:89], v[66:69], v[22:25]
	v_mfma_f32_16x16x32_bf16 v[26:29], v[90:93], v[66:69], v[18:21]
	v_mfma_f32_16x16x32_bf16 v[22:25], v[102:105], v[66:69], v[14:17]
	v_mfma_f32_16x16x32_bf16 v[18:21], v[94:97], v[66:69], v[10:13]
	v_lshrrev_b32_e32 v67, 2, v0
	v_and_b32_e32 v66, 64, v0
	v_and_b32_e32 v67, 12, v67
	v_or3_b32 v66, v66, v67, s8
	v_ashrrev_i32_e32 v67, 1, v0
	v_mfma_f32_16x16x32_bf16 v[14:17], v[86:89], v[78:81], v[6:9]
	v_and_b32_e32 v67, 0xffffffc0, v67
	v_add_u32_e32 v67, s6, v67
	v_and_or_b32 v0, v0, 15, v67
	v_mfma_f32_16x16x32_bf16 v[10:13], v[90:93], v[78:81], v[2:5]
	v_mov_b64_e32 v[68:69], s[4:5]
	v_mad_i64_i32 v[68:69], s[6:7], v0, s33, v[68:69]
	v_mfma_f32_16x16x32_bf16 v[2:5], v[102:105], v[78:81], v[70:73]
	v_cmp_gt_i32_e32 vcc, s63, v66
	v_ashrrev_i32_e32 v67, 31, v66
	v_mfma_f32_16x16x32_bf16 v[6:9], v[94:97], v[78:81], v[74:77]
	s_and_saveexec_b64 s[6:7], vcc
	s_cbranch_execz .LBB0_813
	v_lshl_add_u64 v[70:71], v[66:67], 1, v[68:69]
	v_cvt_pk_bf16_f32 v65, v64, v65
	v_cvt_pk_bf16_f32 v64, v62, v63
	global_store_dwordx2 v[70:71], v[64:65], off
